# GEMM K loops: barrier-to-MFMA handoff trimmed (priority raised before parking at the barrier, repeated lgkmcnt wait behind it dropped, closing barrier reached before the priority drop)
# speedup vs baseline: 1.0038x; 1.0033x over previous
; #define PG8_STAGE(bufoff, gbase, voff) do { _Pragma("unroll") for (int _i = 0; _i < 2; ++_i) \
;         __builtin_amdgcn_global_load_lds((const unsigned*)((const char*)(gbase) + (voff)[_i]), (PG8_LAS unsigned*)(lds + (bufoff) + ldsw + _i * 8192), 16, 0, 0); } while (0)
; #define PG8_LDA(dst, b, h) do { _Pragma("unroll") for (int m = 0; m < 4; ++m) _Pragma("unroll") for (int k = 0; k < 2; ++k) dst[m][k] = *(const PG8_LAS bf16x8*)(lds + PG8_SA(b, h) + aoff + m * 2048 + k * 1024); } while (0)
; #define PG8_LDB(dst, b, h) do { _Pragma("unroll") for (int n = 0; n < 2; ++n) _Pragma("unroll") for (int k = 0; k < 2; ++k) dst[n][k] = *(const PG8_LAS bf16x8*)(lds + PG8_SB(b, h) + boff + n * 2048 + k * 1024); } while (0)
; #define PG8_MMA(ai, bj, At, Bt) do { __builtin_amdgcn_s_setprio(1); _Pragma("unroll") for (int m = 0; m < 4; ++m) _Pragma("unroll") for (int n = 0; n < 2; ++n) _Pragma("unroll") for (int k = 0; k < 2; ++k) \
;         acc[ai][bj][m][n] = __builtin_amdgcn_mfma_f32_16x16x32_bf16(Bt[n][k], At[m][k], acc[ai][bj][m][n], 0, 0, 0); __builtin_amdgcn_s_setprio(0); } while (0)
; #define PG8_WAIT_V(n) asm volatile("s_waitcnt vmcnt(" #n ")" ::: "memory")
; #define PG8_WAIT_L(n) asm volatile("s_waitcnt lgkmcnt(" #n ")" ::: "memory")
; #define PG8_BAR __builtin_amdgcn_s_barrier()
; #define PG8_SCHED __builtin_amdgcn_sched_barrier(0)
; template <class Epi, class Sched, bool ALIGN_EPI = false, bool SP2 = false>
; __device__ __forceinline__ void gemm_phase(PG8_LAS unsigned char* lds, const Gemm g, const Sched& S, const Epi& E) {
;     ...
;             if constexpr (SP2) {
;             PG8_LDB(B0, 0, 0); PG8_LDB(B1, 0, 1); PG8_SCHED; PG8_LDA(At, 0, 0); PG8_STAGE(PG8_SA(1, 1), a1 + hstep, voffA);
;             PG8_WAIT_V(8); PG8_WAIT_L(0); PG8_BAR; PG8_MMA(0, 0, At, B0); PG8_MMA(0, 1, At, B1); PG8_BAR; PG8_SCHED;
;             PG8_LDA(At, 0, 1); PG8_STAGE(PG8_SB(0, 0), b2, voffB); PG8_STAGE(PG8_SB(0, 1), b2 + hstep, voffB); PG8_STAGE(PG8_SA(0, 0), a2, voffA);
;             PG8_WAIT_V(8); PG8_WAIT_L(0); PG8_BAR; PG8_MMA(1, 0, At, B0); PG8_MMA(1, 1, At, B1); PG8_BAR; PG8_SCHED;
.LBB0_38:
	s_add_u32 s10, vcc_lo, 0xfff80080
	s_addc_u32 s11, vcc_hi, -1
	s_add_i32 s84, 0, 0x10000
	s_cmp_eq_u32 s13, 28
	s_cselect_b32 s69, s27, s11
	s_cselect_b32 s68, s86, s10
	s_cselect_b32 s11, s17, s12
	s_cselect_b32 s10, s88, s21
	s_add_i32 s93, 0, 0x14000
	v_add_u32_e32 v138, s84, v194
	v_add_u32_e32 v164, s93, v194
	ds_read_b128 v[114:117], v138
	ds_read_b128 v[118:121], v138 offset:1024
	ds_read_b128 v[130:133], v138 offset:2048
	ds_read_b128 v[138:141], v138 offset:3072
	ds_read_b128 v[146:149], v164
	ds_read_b128 v[156:159], v164 offset:1024
	ds_read_b128 v[160:163], v164 offset:2048
	ds_read_b128 v[164:167], v164 offset:3072
	v_lshl_add_u64 v[208:209], vcc, 0, v[152:153]
	s_add_i32 m0, s2, 0xc000
	ds_read_b128 v[168:171], v199
	ds_read_b128 v[172:175], v199 offset:1024
	ds_read_b128 v[176:179], v199 offset:2048
	ds_read_b128 v[180:183], v199 offset:3072
	ds_read_b128 v[184:187], v199 offset:4096
	ds_read_b128 v[188:191], v199 offset:5120
	ds_read_b128 v[200:203], v199 offset:6144
	ds_read_b128 v[204:207], v199 offset:7168
	global_load_lds_dwordx4 v[208:209], off
	v_lshl_add_u64 v[208:209], vcc, 0, v[154:155]
	s_add_i32 m0, s2, 0xe000
	s_nop 0
	global_load_lds_dwordx4 v[208:209], off
	s_waitcnt vmcnt(8)
	s_waitcnt lgkmcnt(0)
	s_setprio 1
	s_barrier
	v_mfma_f32_16x16x32_bf16 v[142:145], v[114:117], v[168:171], v[142:145]
	v_mfma_f32_16x16x32_bf16 v[62:65], v[130:133], v[168:171], v[62:65]
	v_mfma_f32_16x16x32_bf16 v[122:125], v[114:117], v[176:179], v[122:125]
	v_mfma_f32_16x16x32_bf16 v[50:53], v[130:133], v[176:179], v[50:53]
	v_mfma_f32_16x16x32_bf16 v[106:109], v[114:117], v[184:187], v[106:109]
	v_mfma_f32_16x16x32_bf16 v[42:45], v[130:133], v[184:187], v[42:45]
	v_mfma_f32_16x16x32_bf16 v[98:101], v[114:117], v[200:203], v[98:101]
	v_mfma_f32_16x16x32_bf16 v[34:37], v[130:133], v[200:203], v[34:37]
	v_mfma_f32_16x16x32_bf16 v[142:145], v[118:121], v[172:175], v[142:145]
	v_mfma_f32_16x16x32_bf16 v[62:65], v[138:141], v[172:175], v[62:65]
	v_mfma_f32_16x16x32_bf16 v[122:125], v[118:121], v[180:183], v[122:125]
	v_mfma_f32_16x16x32_bf16 v[50:53], v[138:141], v[180:183], v[50:53]
	v_mfma_f32_16x16x32_bf16 v[106:109], v[118:121], v[188:191], v[106:109]
	v_mfma_f32_16x16x32_bf16 v[42:45], v[138:141], v[188:191], v[42:45]
	v_mfma_f32_16x16x32_bf16 v[98:101], v[118:121], v[204:207], v[98:101]
	v_mfma_f32_16x16x32_bf16 v[34:37], v[138:141], v[204:207], v[34:37]
	s_setprio 0
	s_setprio 1
	v_mfma_f32_16x16x32_bf16 v[134:137], v[146:149], v[168:171], v[134:137]
	v_mfma_f32_16x16x32_bf16 v[58:61], v[160:163], v[168:171], v[58:61]
	v_mfma_f32_16x16x32_bf16 v[126:129], v[146:149], v[176:179], v[126:129]
	v_mfma_f32_16x16x32_bf16 v[54:57], v[160:163], v[176:179], v[54:57]
	v_mfma_f32_16x16x32_bf16 v[110:113], v[146:149], v[184:187], v[110:113]
	v_mfma_f32_16x16x32_bf16 v[46:49], v[160:163], v[184:187], v[46:49]
	v_mfma_f32_16x16x32_bf16 v[102:105], v[146:149], v[200:203], v[102:105]
	v_mfma_f32_16x16x32_bf16 v[38:41], v[160:163], v[200:203], v[38:41]
	v_mfma_f32_16x16x32_bf16 v[134:137], v[156:159], v[172:175], v[134:137]
	v_mfma_f32_16x16x32_bf16 v[58:61], v[164:167], v[172:175], v[58:61]
	v_mfma_f32_16x16x32_bf16 v[126:129], v[156:159], v[180:183], v[126:129]
	v_mfma_f32_16x16x32_bf16 v[54:57], v[164:167], v[180:183], v[54:57]
	v_mfma_f32_16x16x32_bf16 v[110:113], v[156:159], v[188:191], v[110:113]
	v_mfma_f32_16x16x32_bf16 v[46:49], v[164:167], v[188:191], v[46:49]
	v_mfma_f32_16x16x32_bf16 v[102:105], v[156:159], v[204:207], v[102:105]
	v_mfma_f32_16x16x32_bf16 v[38:41], v[164:167], v[204:207], v[38:41]
	s_barrier
	s_setprio 0
	s_add_i32 s84, s84, s1
	v_lshl_add_u64 v[208:209], s[10:11], 0, v[0:1]
	s_mov_b32 m0, s84
	ds_read_b128 v[168:171], v199 offset:16384
	ds_read_b128 v[172:175], v199 offset:17408
	ds_read_b128 v[176:179], v199 offset:18432
	ds_read_b128 v[180:183], v199 offset:19456
	ds_read_b128 v[184:187], v199 offset:20480
	ds_read_b128 v[188:191], v199 offset:21504
	ds_read_b128 v[200:203], v199 offset:22528
	ds_read_b128 v[204:207], v199 offset:23552
	global_load_lds_dwordx4 v[208:209], off
	s_add_i32 m0, s84, 0x2000
	s_add_u32 s84, s10, 0x80000
	v_lshl_add_u64 v[210:211], s[10:11], 0, v[150:151]
	s_addc_u32 s85, s11, 0
	s_add_i32 s93, s93, s1
	global_load_lds_dwordx4 v[210:211], off
	v_lshl_add_u64 v[212:213], s[84:85], 0, v[0:1]
	s_mov_b32 m0, s93
	v_lshl_add_u64 v[214:215], s[68:69], 0, v[150:151]
	global_load_lds_dwordx4 v[212:213], off
	v_lshl_add_u64 v[212:213], s[84:85], 0, v[150:151]
	s_add_i32 m0, s93, 0x2000
	s_nop 0
	global_load_lds_dwordx4 v[212:213], off
	v_lshl_add_u64 v[212:213], s[68:69], 0, v[0:1]
	s_mov_b32 m0, s2
	s_nop 0
	global_load_lds_dwordx4 v[212:213], off
	s_mov_b32 m0, s4
	s_nop 0
	global_load_lds_dwordx4 v[214:215], off
	s_waitcnt vmcnt(8)
	s_waitcnt lgkmcnt(0)
	s_setprio 1
	s_barrier
; #define PG8_STAGE(bufoff, gbase, voff) do { _Pragma("unroll") for (int _i = 0; _i < 2; ++_i) \
;         __builtin_amdgcn_global_load_lds((const unsigned*)((const char*)(gbase) + (voff)[_i]), (PG8_LAS unsigned*)(lds + (bufoff) + ldsw + _i * 8192), 16, 0, 0); } while (0)
; #define PG8_LDA(dst, b, h) do { _Pragma("unroll") for (int m = 0; m < 4; ++m) _Pragma("unroll") for (int k = 0; k < 2; ++k) dst[m][k] = *(const PG8_LAS bf16x8*)(lds + PG8_SA(b, h) + aoff + m * 2048 + k * 1024); } while (0)
; #define PG8_LDB(dst, b, h) do { _Pragma("unroll") for (int n = 0; n < 2; ++n) _Pragma("unroll") for (int k = 0; k < 2; ++k) dst[n][k] = *(const PG8_LAS bf16x8*)(lds + PG8_SB(b, h) + boff + n * 2048 + k * 1024); } while (0)
; #define PG8_MMA(ai, bj, At, Bt) do { __builtin_amdgcn_s_setprio(1); _Pragma("unroll") for (int m = 0; m < 4; ++m) _Pragma("unroll") for (int n = 0; n < 2; ++n) _Pragma("unroll") for (int k = 0; k < 2; ++k) \
;         acc[ai][bj][m][n] = __builtin_amdgcn_mfma_f32_16x16x32_bf16(Bt[n][k], At[m][k], acc[ai][bj][m][n], 0, 0, 0); __builtin_amdgcn_s_setprio(0); } while (0)
; #define PG8_WAIT_V(n) asm volatile("s_waitcnt vmcnt(" #n ")" ::: "memory")
; #define PG8_WAIT_L(n) asm volatile("s_waitcnt lgkmcnt(" #n ")" ::: "memory")
; #define PG8_BAR __builtin_amdgcn_s_barrier()
; #define PG8_SCHED __builtin_amdgcn_sched_barrier(0)
; template <class Epi, class Sched, bool ALIGN_EPI = false, bool SP2 = false>
; __device__ __forceinline__ void gemm_phase(PG8_LAS unsigned char* lds, const Gemm g, const Sched& S, const Epi& E) {
;     ...
;             PG8_LDA(At, 0, 1); PG8_STAGE(PG8_SB(0, 0), b2, voffB); PG8_STAGE(PG8_SB(0, 1), b2 + hstep, voffB); PG8_STAGE(PG8_SA(0, 0), a2, voffA);
;             PG8_WAIT_V(8); PG8_WAIT_L(0); PG8_BAR; PG8_MMA(1, 0, At, B0); PG8_MMA(1, 1, At, B1); PG8_BAR; PG8_SCHED;
;             PG8_LDB(B0, 1, 0); PG8_LDB(B1, 1, 1); PG8_SCHED; PG8_LDA(At, 1, 0); PG8_STAGE(PG8_SA(0, 1), a2 + hstep, voffA);
;             PG8_WAIT_V(8); PG8_WAIT_L(0); PG8_BAR; PG8_MMA(0, 0, At, B0); PG8_MMA(0, 1, At, B1); PG8_BAR; PG8_SCHED;
	v_mfma_f32_16x16x32_bf16 v[94:97], v[114:117], v[168:171], v[94:97]
	v_mfma_f32_16x16x32_bf16 v[30:33], v[130:133], v[168:171], v[30:33]
	v_mfma_f32_16x16x32_bf16 v[82:85], v[114:117], v[176:179], v[82:85]
	v_mfma_f32_16x16x32_bf16 v[18:21], v[130:133], v[176:179], v[18:21]
	v_mfma_f32_16x16x32_bf16 v[74:77], v[114:117], v[184:187], v[74:77]
	v_mfma_f32_16x16x32_bf16 v[10:13], v[130:133], v[184:187], v[10:13]
	v_mfma_f32_16x16x32_bf16 v[66:69], v[114:117], v[200:203], v[66:69]
	v_mfma_f32_16x16x32_bf16 v[2:5], v[130:133], v[200:203], v[2:5]
	v_mfma_f32_16x16x32_bf16 v[94:97], v[118:121], v[172:175], v[94:97]
	v_mfma_f32_16x16x32_bf16 v[30:33], v[138:141], v[172:175], v[30:33]
	v_mfma_f32_16x16x32_bf16 v[82:85], v[118:121], v[180:183], v[82:85]
	v_mfma_f32_16x16x32_bf16 v[18:21], v[138:141], v[180:183], v[18:21]
	v_mfma_f32_16x16x32_bf16 v[74:77], v[118:121], v[188:191], v[74:77]
	v_mfma_f32_16x16x32_bf16 v[10:13], v[138:141], v[188:191], v[10:13]
	v_mfma_f32_16x16x32_bf16 v[66:69], v[118:121], v[204:207], v[66:69]
	v_mfma_f32_16x16x32_bf16 v[2:5], v[138:141], v[204:207], v[2:5]
	s_setprio 0
	s_setprio 1
	v_mfma_f32_16x16x32_bf16 v[90:93], v[146:149], v[168:171], v[90:93]
	v_mfma_f32_16x16x32_bf16 v[26:29], v[160:163], v[168:171], v[26:29]
	v_mfma_f32_16x16x32_bf16 v[86:89], v[146:149], v[176:179], v[86:89]
	v_mfma_f32_16x16x32_bf16 v[22:25], v[160:163], v[176:179], v[22:25]
	v_mfma_f32_16x16x32_bf16 v[78:81], v[146:149], v[184:187], v[78:81]
	v_mfma_f32_16x16x32_bf16 v[14:17], v[160:163], v[184:187], v[14:17]
	v_mfma_f32_16x16x32_bf16 v[70:73], v[146:149], v[200:203], v[70:73]
	v_mfma_f32_16x16x32_bf16 v[6:9], v[160:163], v[200:203], v[6:9]
	v_mfma_f32_16x16x32_bf16 v[90:93], v[156:159], v[172:175], v[90:93]
	v_mfma_f32_16x16x32_bf16 v[26:29], v[164:167], v[172:175], v[26:29]
	v_mfma_f32_16x16x32_bf16 v[86:89], v[156:159], v[180:183], v[86:89]
	v_mfma_f32_16x16x32_bf16 v[22:25], v[164:167], v[180:183], v[22:25]
	v_mfma_f32_16x16x32_bf16 v[78:81], v[156:159], v[188:191], v[78:81]
	v_mfma_f32_16x16x32_bf16 v[14:17], v[164:167], v[188:191], v[14:17]
	v_mfma_f32_16x16x32_bf16 v[70:73], v[156:159], v[204:207], v[70:73]
	v_mfma_f32_16x16x32_bf16 v[6:9], v[164:167], v[204:207], v[6:9]
	s_barrier
	s_setprio 0
	s_add_i32 s84, 0, 0x18000
	s_add_i32 s85, 0, 0x1c000
	v_add_u32_e32 v138, s84, v194
	v_add_u32_e32 v164, s85, v194
	ds_read_b128 v[114:117], v138
	ds_read_b128 v[118:121], v138 offset:1024
	ds_read_b128 v[130:133], v138 offset:2048
	ds_read_b128 v[138:141], v138 offset:3072
	ds_read_b128 v[146:149], v164
	ds_read_b128 v[156:159], v164 offset:1024
	ds_read_b128 v[160:163], v164 offset:2048
	ds_read_b128 v[164:167], v164 offset:3072
	s_add_u32 s68, s68, 0x80000
	s_addc_u32 s69, s69, 0
	s_mov_b32 m0, s5
	v_lshl_add_u64 v[216:217], s[68:69], 0, v[0:1]
	ds_read_b128 v[168:171], v199 offset:32768
	ds_read_b128 v[172:175], v199 offset:33792
	ds_read_b128 v[176:179], v199 offset:34816
	ds_read_b128 v[180:183], v199 offset:35840
	ds_read_b128 v[184:187], v199 offset:36864
	ds_read_b128 v[188:191], v199 offset:37888
	ds_read_b128 v[200:203], v199 offset:38912
	ds_read_b128 v[204:207], v199 offset:39936
	global_load_lds_dwordx4 v[216:217], off
	v_lshl_add_u64 v[216:217], s[68:69], 0, v[150:151]
	s_mov_b32 m0, s6
	s_nop 0
	global_load_lds_dwordx4 v[216:217], off
	s_waitcnt vmcnt(8)
	s_waitcnt lgkmcnt(0)
	s_setprio 1
	s_barrier
	v_mfma_f32_16x16x32_bf16 v[142:145], v[114:117], v[168:171], v[142:145]
	v_mfma_f32_16x16x32_bf16 v[62:65], v[130:133], v[168:171], v[62:65]
	v_mfma_f32_16x16x32_bf16 v[122:125], v[114:117], v[176:179], v[122:125]
	v_mfma_f32_16x16x32_bf16 v[50:53], v[130:133], v[176:179], v[50:53]
	v_mfma_f32_16x16x32_bf16 v[106:109], v[114:117], v[184:187], v[106:109]
	v_mfma_f32_16x16x32_bf16 v[42:45], v[130:133], v[184:187], v[42:45]
	v_mfma_f32_16x16x32_bf16 v[98:101], v[114:117], v[200:203], v[98:101]
	v_mfma_f32_16x16x32_bf16 v[34:37], v[130:133], v[200:203], v[34:37]
	v_mfma_f32_16x16x32_bf16 v[142:145], v[118:121], v[172:175], v[142:145]
	v_mfma_f32_16x16x32_bf16 v[62:65], v[138:141], v[172:175], v[62:65]
	v_mfma_f32_16x16x32_bf16 v[122:125], v[118:121], v[180:183], v[122:125]
	v_mfma_f32_16x16x32_bf16 v[50:53], v[138:141], v[180:183], v[50:53]
	v_mfma_f32_16x16x32_bf16 v[106:109], v[118:121], v[188:191], v[106:109]
	v_mfma_f32_16x16x32_bf16 v[42:45], v[138:141], v[188:191], v[42:45]
	v_mfma_f32_16x16x32_bf16 v[98:101], v[118:121], v[204:207], v[98:101]
	v_mfma_f32_16x16x32_bf16 v[34:37], v[138:141], v[204:207], v[34:37]
	s_setprio 0
	s_setprio 1
	v_mfma_f32_16x16x32_bf16 v[134:137], v[146:149], v[168:171], v[134:137]
	v_mfma_f32_16x16x32_bf16 v[58:61], v[160:163], v[168:171], v[58:61]
	v_mfma_f32_16x16x32_bf16 v[126:129], v[146:149], v[176:179], v[126:129]
	v_mfma_f32_16x16x32_bf16 v[54:57], v[160:163], v[176:179], v[54:57]
	v_mfma_f32_16x16x32_bf16 v[110:113], v[146:149], v[184:187], v[110:113]
	v_mfma_f32_16x16x32_bf16 v[46:49], v[160:163], v[184:187], v[46:49]
	v_mfma_f32_16x16x32_bf16 v[102:105], v[146:149], v[200:203], v[102:105]
	v_mfma_f32_16x16x32_bf16 v[38:41], v[160:163], v[200:203], v[38:41]
	v_mfma_f32_16x16x32_bf16 v[134:137], v[156:159], v[172:175], v[134:137]
	v_mfma_f32_16x16x32_bf16 v[58:61], v[164:167], v[172:175], v[58:61]
	v_mfma_f32_16x16x32_bf16 v[126:129], v[156:159], v[180:183], v[126:129]
	v_mfma_f32_16x16x32_bf16 v[54:57], v[164:167], v[180:183], v[54:57]
	v_mfma_f32_16x16x32_bf16 v[110:113], v[156:159], v[188:191], v[110:113]
	v_mfma_f32_16x16x32_bf16 v[46:49], v[164:167], v[188:191], v[46:49]
	v_mfma_f32_16x16x32_bf16 v[102:105], v[156:159], v[204:207], v[102:105]
	v_mfma_f32_16x16x32_bf16 v[38:41], v[164:167], v[204:207], v[38:41]
	s_barrier
; #define PG8_STAGE(bufoff, gbase, voff) do { _Pragma("unroll") for (int _i = 0; _i < 2; ++_i) \
;         __builtin_amdgcn_global_load_lds((const unsigned*)((const char*)(gbase) + (voff)[_i]), (PG8_LAS unsigned*)(lds + (bufoff) + ldsw + _i * 8192), 16, 0, 0); } while (0)
; #define PG8_LDA(dst, b, h) do { _Pragma("unroll") for (int m = 0; m < 4; ++m) _Pragma("unroll") for (int k = 0; k < 2; ++k) dst[m][k] = *(const PG8_LAS bf16x8*)(lds + PG8_SA(b, h) + aoff + m * 2048 + k * 1024); } while (0)
; #define PG8_MMA(ai, bj, At, Bt) do { __builtin_amdgcn_s_setprio(1); _Pragma("unroll") for (int m = 0; m < 4; ++m) _Pragma("unroll") for (int n = 0; n < 2; ++n) _Pragma("unroll") for (int k = 0; k < 2; ++k) \
;         acc[ai][bj][m][n] = __builtin_amdgcn_mfma_f32_16x16x32_bf16(Bt[n][k], At[m][k], acc[ai][bj][m][n], 0, 0, 0); __builtin_amdgcn_s_setprio(0); } while (0)
; #define PG8_WAIT_V(n) asm volatile("s_waitcnt vmcnt(" #n ")" ::: "memory")
; #define PG8_WAIT_L(n) asm volatile("s_waitcnt lgkmcnt(" #n ")" ::: "memory")
; #define PG8_BAR __builtin_amdgcn_s_barrier()
; #define PG8_SCHED __builtin_amdgcn_sched_barrier(0)
; template <class Epi, class Sched, bool ALIGN_EPI = false, bool SP2 = false>
; __device__ __forceinline__ void gemm_phase(PG8_LAS unsigned char* lds, const Gemm g, const Sched& S, const Epi& E) {
;     ...
;         for (int t = 0; t < nt; t += 2) {
;             const bool last = (t == nt - 2);
;     ...
;             PG8_WAIT_V(8); PG8_WAIT_L(0); PG8_BAR; PG8_MMA(0, 0, At, B0); PG8_MMA(0, 1, At, B1); PG8_BAR; PG8_SCHED;
;             PG8_LDA(At, 1, 1); PG8_STAGE(PG8_SB(1, 0), b3, voffB); PG8_STAGE(PG8_SB(1, 1), b3 + hstep, voffB); PG8_STAGE(PG8_SA(1, 0), a3, voffA);
;             PG8_WAIT_V(8); PG8_WAIT_L(0); PG8_BAR; PG8_MMA(1, 0, At, B0); PG8_MMA(1, 1, At, B1); PG8_BAR; PG8_SCHED;
	s_setprio 0
	s_add_i32 s68, s84, s1
	v_lshl_add_u64 v[208:209], v[208:209], 0, s[34:35]
	s_mov_b32 m0, s68
	ds_read_b128 v[168:171], v199 offset:49152
	ds_read_b128 v[172:175], v199 offset:50176
	ds_read_b128 v[176:179], v199 offset:51200
	ds_read_b128 v[180:183], v199 offset:52224
	ds_read_b128 v[184:187], v199 offset:53248
	ds_read_b128 v[188:191], v199 offset:54272
	ds_read_b128 v[200:203], v199 offset:55296
	ds_read_b128 v[204:207], v199 offset:56320
	global_load_lds_dwordx4 v[208:209], off
	s_add_i32 m0, s68, 0x2000
	s_add_u32 s10, s10, 0x80080
	v_lshl_add_u64 v[208:209], v[210:211], 0, s[34:35]
	s_addc_u32 s11, s11, 0
	s_add_i32 s68, s85, s1
	global_load_lds_dwordx4 v[208:209], off
	v_lshl_add_u64 v[208:209], s[10:11], 0, v[0:1]
	s_mov_b32 m0, s68
	s_nop 0
	global_load_lds_dwordx4 v[208:209], off
	v_lshl_add_u64 v[208:209], s[10:11], 0, v[150:151]
	s_add_i32 m0, s68, 0x2000
	s_nop 0
	global_load_lds_dwordx4 v[208:209], off
	v_lshl_add_u64 v[208:209], v[212:213], 0, s[34:35]
	s_mov_b32 m0, s7
	s_nop 0
	global_load_lds_dwordx4 v[208:209], off
	v_lshl_add_u64 v[208:209], v[214:215], 0, s[34:35]
	s_mov_b32 m0, s30
	s_nop 0
	global_load_lds_dwordx4 v[208:209], off
	s_waitcnt vmcnt(8)
	s_waitcnt lgkmcnt(0)
	s_setprio 1
	s_barrier
	v_mfma_f32_16x16x32_bf16 v[94:97], v[114:117], v[168:171], v[94:97]
	v_mfma_f32_16x16x32_bf16 v[30:33], v[130:133], v[168:171], v[30:33]
	v_mfma_f32_16x16x32_bf16 v[82:85], v[114:117], v[176:179], v[82:85]
	v_mfma_f32_16x16x32_bf16 v[18:21], v[130:133], v[176:179], v[18:21]
	v_mfma_f32_16x16x32_bf16 v[74:77], v[114:117], v[184:187], v[74:77]
	v_mfma_f32_16x16x32_bf16 v[10:13], v[130:133], v[184:187], v[10:13]
	v_mfma_f32_16x16x32_bf16 v[66:69], v[114:117], v[200:203], v[66:69]
	v_mfma_f32_16x16x32_bf16 v[2:5], v[130:133], v[200:203], v[2:5]
	v_mfma_f32_16x16x32_bf16 v[94:97], v[118:121], v[172:175], v[94:97]
	v_mfma_f32_16x16x32_bf16 v[30:33], v[138:141], v[172:175], v[30:33]
	v_mfma_f32_16x16x32_bf16 v[82:85], v[118:121], v[180:183], v[82:85]
	v_mfma_f32_16x16x32_bf16 v[18:21], v[138:141], v[180:183], v[18:21]
	v_mfma_f32_16x16x32_bf16 v[74:77], v[118:121], v[188:191], v[74:77]
	v_mfma_f32_16x16x32_bf16 v[10:13], v[138:141], v[188:191], v[10:13]
	v_mfma_f32_16x16x32_bf16 v[66:69], v[118:121], v[204:207], v[66:69]
	v_mfma_f32_16x16x32_bf16 v[2:5], v[138:141], v[204:207], v[2:5]
	s_setprio 0
	s_setprio 1
	v_mfma_f32_16x16x32_bf16 v[90:93], v[146:149], v[168:171], v[90:93]
	v_mfma_f32_16x16x32_bf16 v[26:29], v[160:163], v[168:171], v[26:29]
	v_mfma_f32_16x16x32_bf16 v[86:89], v[146:149], v[176:179], v[86:89]
	v_mfma_f32_16x16x32_bf16 v[22:25], v[160:163], v[176:179], v[22:25]
	v_mfma_f32_16x16x32_bf16 v[78:81], v[146:149], v[184:187], v[78:81]
	v_mfma_f32_16x16x32_bf16 v[14:17], v[160:163], v[184:187], v[14:17]
	v_mfma_f32_16x16x32_bf16 v[70:73], v[146:149], v[200:203], v[70:73]
	v_mfma_f32_16x16x32_bf16 v[6:9], v[160:163], v[200:203], v[6:9]
	v_mfma_f32_16x16x32_bf16 v[90:93], v[156:159], v[172:175], v[90:93]
	v_mfma_f32_16x16x32_bf16 v[26:29], v[164:167], v[172:175], v[26:29]
	v_mfma_f32_16x16x32_bf16 v[86:89], v[156:159], v[180:183], v[86:89]
	v_mfma_f32_16x16x32_bf16 v[22:25], v[164:167], v[180:183], v[22:25]
	v_mfma_f32_16x16x32_bf16 v[78:81], v[156:159], v[188:191], v[78:81]
	v_mfma_f32_16x16x32_bf16 v[14:17], v[164:167], v[188:191], v[14:17]
	v_mfma_f32_16x16x32_bf16 v[70:73], v[156:159], v[204:207], v[70:73]
	v_mfma_f32_16x16x32_bf16 v[6:9], v[164:167], v[204:207], v[6:9]
	s_barrier
	s_setprio 0
	s_add_i32 s13, s13, 2
	s_add_u32 vcc_lo, vcc_lo, 0x100
	s_addc_u32 vcc_hi, vcc_hi, 0
	s_add_u32 s21, s21, 0x100
	s_addc_u32 s12, s12, 0
	s_cmp_gt_u32 s13, 29
	s_cbranch_scc0 .LBB0_38
	s_and_b64 vcc, exec, s[58:59]
	s_cbranch_vccz .LBB0_41
	s_barrier

; #define PG8_STAGE(bufoff, gbase, voff) do { _Pragma("unroll") for (int _i = 0; _i < 2; ++_i) \
;         __builtin_amdgcn_global_load_lds((const unsigned*)((const char*)(gbase) + (voff)[_i]), (PG8_LAS unsigned*)(lds + (bufoff) + ldsw + _i * 8192), 16, 0, 0); } while (0)
; #define PG8_LDA(dst, b, h) do { _Pragma("unroll") for (int m = 0; m < 4; ++m) _Pragma("unroll") for (int k = 0; k < 2; ++k) dst[m][k] = *(const PG8_LAS bf16x8*)(lds + PG8_SA(b, h) + aoff + m * 2048 + k * 1024); } while (0)
; #define PG8_LDB(dst, b, h) do { _Pragma("unroll") for (int n = 0; n < 2; ++n) _Pragma("unroll") for (int k = 0; k < 2; ++k) dst[n][k] = *(const PG8_LAS bf16x8*)(lds + PG8_SB(b, h) + boff + n * 2048 + k * 1024); } while (0)
; #define PG8_MMA(ai, bj, At, Bt) do { __builtin_amdgcn_s_setprio(1); _Pragma("unroll") for (int m = 0; m < 4; ++m) _Pragma("unroll") for (int n = 0; n < 2; ++n) _Pragma("unroll") for (int k = 0; k < 2; ++k) \
;         acc[ai][bj][m][n] = __builtin_amdgcn_mfma_f32_16x16x32_bf16(Bt[n][k], At[m][k], acc[ai][bj][m][n], 0, 0, 0); __builtin_amdgcn_s_setprio(0); } while (0)
; #define PG8_WAIT_V(n) asm volatile("s_waitcnt vmcnt(" #n ")" ::: "memory")
; #define PG8_WAIT_L(n) asm volatile("s_waitcnt lgkmcnt(" #n ")" ::: "memory")
; #define PG8_BAR __builtin_amdgcn_s_barrier()
; #define PG8_SCHED __builtin_amdgcn_sched_barrier(0)
; template <class Epi, class Sched, bool ALIGN_EPI = false, bool SP2 = false>
; __device__ __forceinline__ void gemm_phase(PG8_LAS unsigned char* lds, const Gemm g, const Sched& S, const Epi& E) {
;     ...
;             if constexpr (SP2) {
;             PG8_LDB(B0, 0, 0); PG8_LDB(B1, 0, 1); PG8_SCHED; PG8_LDA(At, 0, 0); PG8_STAGE(PG8_SA(1, 1), a1 + hstep, voffA);
;             PG8_WAIT_V(8); PG8_WAIT_L(0); PG8_BAR; PG8_MMA(0, 0, At, B0); PG8_MMA(0, 1, At, B1); PG8_BAR; PG8_SCHED;
;             PG8_LDA(At, 0, 1); PG8_STAGE(PG8_SB(0, 0), b2, voffB); PG8_STAGE(PG8_SB(0, 1), b2 + hstep, voffB); PG8_STAGE(PG8_SA(0, 0), a2, voffA);
;             PG8_WAIT_V(8); PG8_WAIT_L(0); PG8_BAR; PG8_MMA(1, 0, At, B0); PG8_MMA(1, 1, At, B1); PG8_BAR; PG8_SCHED;
.LBB0_169:
	s_add_u32 s10, s16, 0xfff80080
	s_addc_u32 s11, s17, -1
	s_add_i32 s21, 0, 0x10000
	s_cmp_eq_u32 s13, 28
	s_cselect_b32 s57, s43, s11
	s_cselect_b32 s56, s47, s10
	v_add_u32_e32 v148, s21, v151
	s_cselect_b32 s11, s45, s12
	s_cselect_b32 s10, s60, s61
	s_add_i32 s64, 0, 0x14000
	ds_read_b128 v[140:143], v148
	ds_read_b128 v[144:147], v148 offset:1024
	ds_read_b128 v[154:157], v148 offset:2048
	ds_read_b128 v[158:161], v148 offset:3072
	v_add_u32_e32 v148, s64, v151
	ds_read_b128 v[162:165], v148
	ds_read_b128 v[166:169], v148 offset:1024
	ds_read_b128 v[170:173], v148 offset:2048
	ds_read_b128 v[174:177], v148 offset:3072
	v_lshl_add_u64 v[210:211], s[16:17], 0, v[136:137]
	s_add_i32 m0, s2, 0xc000
	ds_read_b128 v[178:181], v153
	ds_read_b128 v[182:185], v153 offset:1024
	ds_read_b128 v[186:189], v153 offset:2048
	ds_read_b128 v[190:193], v153 offset:3072
	ds_read_b128 v[194:197], v153 offset:4096
	ds_read_b128 v[198:201], v153 offset:5120
	ds_read_b128 v[202:205], v153 offset:6144
	ds_read_b128 v[206:209], v153 offset:7168
	global_load_lds_dwordx4 v[210:211], off
	v_lshl_add_u64 v[210:211], s[16:17], 0, v[138:139]
	s_add_i32 m0, s2, 0xe000
	s_nop 0
	global_load_lds_dwordx4 v[210:211], off
	s_waitcnt vmcnt(8)
	s_waitcnt lgkmcnt(0)
	s_setprio 1
	s_barrier
	v_mfma_f32_16x16x32_bf16 v[126:129], v[140:143], v[178:181], v[126:129]
	v_mfma_f32_16x16x32_bf16 v[122:125], v[154:157], v[178:181], v[122:125]
	v_mfma_f32_16x16x32_bf16 v[110:113], v[140:143], v[186:189], v[110:113]
	v_mfma_f32_16x16x32_bf16 v[106:109], v[154:157], v[186:189], v[106:109]
	v_mfma_f32_16x16x32_bf16 v[94:97], v[140:143], v[194:197], v[94:97]
	v_mfma_f32_16x16x32_bf16 v[90:93], v[154:157], v[194:197], v[90:93]
	v_mfma_f32_16x16x32_bf16 v[78:81], v[140:143], v[202:205], v[78:81]
	v_mfma_f32_16x16x32_bf16 v[74:77], v[154:157], v[202:205], v[74:77]
	v_mfma_f32_16x16x32_bf16 v[126:129], v[144:147], v[182:185], v[126:129]
	v_mfma_f32_16x16x32_bf16 v[122:125], v[158:161], v[182:185], v[122:125]
	v_mfma_f32_16x16x32_bf16 v[110:113], v[144:147], v[190:193], v[110:113]
	v_mfma_f32_16x16x32_bf16 v[106:109], v[158:161], v[190:193], v[106:109]
	v_mfma_f32_16x16x32_bf16 v[94:97], v[144:147], v[198:201], v[94:97]
	v_mfma_f32_16x16x32_bf16 v[90:93], v[158:161], v[198:201], v[90:93]
	v_mfma_f32_16x16x32_bf16 v[78:81], v[144:147], v[206:209], v[78:81]
	v_mfma_f32_16x16x32_bf16 v[74:77], v[158:161], v[206:209], v[74:77]
	s_setprio 0
	s_setprio 1
	v_mfma_f32_16x16x32_bf16 v[118:121], v[162:165], v[178:181], v[118:121]
	v_mfma_f32_16x16x32_bf16 v[114:117], v[170:173], v[178:181], v[114:117]
	v_mfma_f32_16x16x32_bf16 v[102:105], v[162:165], v[186:189], v[102:105]
	v_mfma_f32_16x16x32_bf16 v[98:101], v[170:173], v[186:189], v[98:101]
	v_mfma_f32_16x16x32_bf16 v[86:89], v[162:165], v[194:197], v[86:89]
	v_mfma_f32_16x16x32_bf16 v[82:85], v[170:173], v[194:197], v[82:85]
	v_mfma_f32_16x16x32_bf16 v[70:73], v[162:165], v[202:205], v[70:73]
	v_mfma_f32_16x16x32_bf16 v[66:69], v[170:173], v[202:205], v[66:69]
	v_mfma_f32_16x16x32_bf16 v[118:121], v[166:169], v[182:185], v[118:121]
	v_mfma_f32_16x16x32_bf16 v[114:117], v[174:177], v[182:185], v[114:117]
	v_mfma_f32_16x16x32_bf16 v[102:105], v[166:169], v[190:193], v[102:105]
	v_mfma_f32_16x16x32_bf16 v[98:101], v[174:177], v[190:193], v[98:101]
	v_mfma_f32_16x16x32_bf16 v[86:89], v[166:169], v[198:201], v[86:89]
	v_mfma_f32_16x16x32_bf16 v[82:85], v[174:177], v[198:201], v[82:85]
	v_mfma_f32_16x16x32_bf16 v[70:73], v[166:169], v[206:209], v[70:73]
	v_mfma_f32_16x16x32_bf16 v[66:69], v[174:177], v[206:209], v[66:69]
	s_barrier
	s_setprio 0
	s_add_i32 s21, s21, s1
	v_lshl_add_u64 v[210:211], s[10:11], 0, v[0:1]
	s_mov_b32 m0, s21
	ds_read_b128 v[178:181], v153 offset:16384
	ds_read_b128 v[182:185], v153 offset:17408
	ds_read_b128 v[186:189], v153 offset:18432
	ds_read_b128 v[190:193], v153 offset:19456
	ds_read_b128 v[194:197], v153 offset:20480
	ds_read_b128 v[198:201], v153 offset:21504
	ds_read_b128 v[202:205], v153 offset:22528
	ds_read_b128 v[206:209], v153 offset:23552
	global_load_lds_dwordx4 v[210:211], off
	s_add_i32 m0, s21, 0x2000
	s_add_u32 s62, s10, 0x80000
	v_lshl_add_u64 v[212:213], s[10:11], 0, v[134:135]
	s_addc_u32 s63, s11, 0
	s_add_i32 s21, s64, s1
	global_load_lds_dwordx4 v[212:213], off
	v_lshl_add_u64 v[214:215], s[62:63], 0, v[0:1]
	s_mov_b32 m0, s21
	v_lshl_add_u64 v[216:217], s[56:57], 0, v[132:133]
	global_load_lds_dwordx4 v[214:215], off
	v_lshl_add_u64 v[214:215], s[62:63], 0, v[134:135]
	s_add_i32 m0, s21, 0x2000
	s_nop 0
	global_load_lds_dwordx4 v[214:215], off
	v_lshl_add_u64 v[214:215], s[56:57], 0, v[130:131]
	s_mov_b32 m0, s2
	s_nop 0
	global_load_lds_dwordx4 v[214:215], off
	s_mov_b32 m0, s4
	s_nop 0
	global_load_lds_dwordx4 v[216:217], off
	s_waitcnt vmcnt(8)
	s_waitcnt lgkmcnt(0)
	s_setprio 1
	s_barrier
; #define PG8_STAGE(bufoff, gbase, voff) do { _Pragma("unroll") for (int _i = 0; _i < 2; ++_i) \
;         __builtin_amdgcn_global_load_lds((const unsigned*)((const char*)(gbase) + (voff)[_i]), (PG8_LAS unsigned*)(lds + (bufoff) + ldsw + _i * 8192), 16, 0, 0); } while (0)
; #define PG8_LDA(dst, b, h) do { _Pragma("unroll") for (int m = 0; m < 4; ++m) _Pragma("unroll") for (int k = 0; k < 2; ++k) dst[m][k] = *(const PG8_LAS bf16x8*)(lds + PG8_SA(b, h) + aoff + m * 2048 + k * 1024); } while (0)
; #define PG8_LDB(dst, b, h) do { _Pragma("unroll") for (int n = 0; n < 2; ++n) _Pragma("unroll") for (int k = 0; k < 2; ++k) dst[n][k] = *(const PG8_LAS bf16x8*)(lds + PG8_SB(b, h) + boff + n * 2048 + k * 1024); } while (0)
; #define PG8_MMA(ai, bj, At, Bt) do { __builtin_amdgcn_s_setprio(1); _Pragma("unroll") for (int m = 0; m < 4; ++m) _Pragma("unroll") for (int n = 0; n < 2; ++n) _Pragma("unroll") for (int k = 0; k < 2; ++k) \
;         acc[ai][bj][m][n] = __builtin_amdgcn_mfma_f32_16x16x32_bf16(Bt[n][k], At[m][k], acc[ai][bj][m][n], 0, 0, 0); __builtin_amdgcn_s_setprio(0); } while (0)
; #define PG8_WAIT_V(n) asm volatile("s_waitcnt vmcnt(" #n ")" ::: "memory")
; #define PG8_WAIT_L(n) asm volatile("s_waitcnt lgkmcnt(" #n ")" ::: "memory")
; #define PG8_BAR __builtin_amdgcn_s_barrier()
; #define PG8_SCHED __builtin_amdgcn_sched_barrier(0)
; template <class Epi, class Sched, bool ALIGN_EPI = false, bool SP2 = false>
; __device__ __forceinline__ void gemm_phase(PG8_LAS unsigned char* lds, const Gemm g, const Sched& S, const Epi& E) {
;     ...
;             PG8_LDA(At, 0, 1); PG8_STAGE(PG8_SB(0, 0), b2, voffB); PG8_STAGE(PG8_SB(0, 1), b2 + hstep, voffB); PG8_STAGE(PG8_SA(0, 0), a2, voffA);
;             PG8_WAIT_V(8); PG8_WAIT_L(0); PG8_BAR; PG8_MMA(1, 0, At, B0); PG8_MMA(1, 1, At, B1); PG8_BAR; PG8_SCHED;
;             PG8_LDB(B0, 1, 0); PG8_LDB(B1, 1, 1); PG8_SCHED; PG8_LDA(At, 1, 0); PG8_STAGE(PG8_SA(0, 1), a2 + hstep, voffA);
;             PG8_WAIT_V(8); PG8_WAIT_L(0); PG8_BAR; PG8_MMA(0, 0, At, B0); PG8_MMA(0, 1, At, B1); PG8_BAR; PG8_SCHED;
	v_mfma_f32_16x16x32_bf16 v[62:65], v[140:143], v[178:181], v[62:65]
	v_mfma_f32_16x16x32_bf16 v[58:61], v[154:157], v[178:181], v[58:61]
	v_mfma_f32_16x16x32_bf16 v[46:49], v[140:143], v[186:189], v[46:49]
	v_mfma_f32_16x16x32_bf16 v[42:45], v[154:157], v[186:189], v[42:45]
	v_mfma_f32_16x16x32_bf16 v[30:33], v[140:143], v[194:197], v[30:33]
	v_mfma_f32_16x16x32_bf16 v[26:29], v[154:157], v[194:197], v[26:29]
	v_mfma_f32_16x16x32_bf16 v[14:17], v[140:143], v[202:205], v[14:17]
	v_mfma_f32_16x16x32_bf16 v[10:13], v[154:157], v[202:205], v[10:13]
	v_mfma_f32_16x16x32_bf16 v[62:65], v[144:147], v[182:185], v[62:65]
	v_mfma_f32_16x16x32_bf16 v[58:61], v[158:161], v[182:185], v[58:61]
	v_mfma_f32_16x16x32_bf16 v[46:49], v[144:147], v[190:193], v[46:49]
	v_mfma_f32_16x16x32_bf16 v[42:45], v[158:161], v[190:193], v[42:45]
	v_mfma_f32_16x16x32_bf16 v[30:33], v[144:147], v[198:201], v[30:33]
	v_mfma_f32_16x16x32_bf16 v[26:29], v[158:161], v[198:201], v[26:29]
	v_mfma_f32_16x16x32_bf16 v[14:17], v[144:147], v[206:209], v[14:17]
	v_mfma_f32_16x16x32_bf16 v[10:13], v[158:161], v[206:209], v[10:13]
	s_setprio 0
	s_setprio 1
	v_mfma_f32_16x16x32_bf16 v[54:57], v[162:165], v[178:181], v[54:57]
	v_mfma_f32_16x16x32_bf16 v[50:53], v[170:173], v[178:181], v[50:53]
	v_mfma_f32_16x16x32_bf16 v[38:41], v[162:165], v[186:189], v[38:41]
	v_mfma_f32_16x16x32_bf16 v[34:37], v[170:173], v[186:189], v[34:37]
	v_mfma_f32_16x16x32_bf16 v[22:25], v[162:165], v[194:197], v[22:25]
	v_mfma_f32_16x16x32_bf16 v[18:21], v[170:173], v[194:197], v[18:21]
	v_mfma_f32_16x16x32_bf16 v[6:9], v[162:165], v[202:205], v[6:9]
	v_mfma_f32_16x16x32_bf16 v[2:5], v[170:173], v[202:205], v[2:5]
	v_mfma_f32_16x16x32_bf16 v[54:57], v[166:169], v[182:185], v[54:57]
	v_mfma_f32_16x16x32_bf16 v[50:53], v[174:177], v[182:185], v[50:53]
	v_mfma_f32_16x16x32_bf16 v[38:41], v[166:169], v[190:193], v[38:41]
	v_mfma_f32_16x16x32_bf16 v[34:37], v[174:177], v[190:193], v[34:37]
	v_mfma_f32_16x16x32_bf16 v[22:25], v[166:169], v[198:201], v[22:25]
	v_mfma_f32_16x16x32_bf16 v[18:21], v[174:177], v[198:201], v[18:21]
	v_mfma_f32_16x16x32_bf16 v[6:9], v[166:169], v[206:209], v[6:9]
	v_mfma_f32_16x16x32_bf16 v[2:5], v[174:177], v[206:209], v[2:5]
	s_barrier
	s_setprio 0
	s_add_i32 s21, 0, 0x18000
	v_add_u32_e32 v148, s21, v151
	s_add_i32 s62, 0, 0x1c000
	ds_read_b128 v[140:143], v148
	ds_read_b128 v[144:147], v148 offset:1024
	ds_read_b128 v[154:157], v148 offset:2048
	ds_read_b128 v[158:161], v148 offset:3072
	v_add_u32_e32 v148, s62, v151
	ds_read_b128 v[162:165], v148
	ds_read_b128 v[166:169], v148 offset:1024
	ds_read_b128 v[170:173], v148 offset:2048
	ds_read_b128 v[174:177], v148 offset:3072
	s_add_u32 s56, s56, 0x80000
	s_addc_u32 s57, s57, 0
	s_mov_b32 m0, s5
	v_lshl_add_u64 v[222:223], s[56:57], 0, v[130:131]
	ds_read_b128 v[178:181], v153 offset:32768
	ds_read_b128 v[182:185], v153 offset:33792
	ds_read_b128 v[186:189], v153 offset:34816
	ds_read_b128 v[190:193], v153 offset:35840
	ds_read_b128 v[194:197], v153 offset:36864
	ds_read_b128 v[198:201], v153 offset:37888
	ds_read_b128 v[202:205], v153 offset:38912
	ds_read_b128 v[206:209], v153 offset:39936
	global_load_lds_dwordx4 v[222:223], off
	v_lshl_add_u64 v[222:223], s[56:57], 0, v[132:133]
	s_mov_b32 m0, s6
	s_nop 0
	global_load_lds_dwordx4 v[222:223], off
	s_waitcnt vmcnt(8)
	s_waitcnt lgkmcnt(0)
	s_setprio 1
	s_barrier
	v_mfma_f32_16x16x32_bf16 v[126:129], v[140:143], v[178:181], v[126:129]
	v_mfma_f32_16x16x32_bf16 v[122:125], v[154:157], v[178:181], v[122:125]
	v_mfma_f32_16x16x32_bf16 v[110:113], v[140:143], v[186:189], v[110:113]
	v_mfma_f32_16x16x32_bf16 v[106:109], v[154:157], v[186:189], v[106:109]
	v_mfma_f32_16x16x32_bf16 v[94:97], v[140:143], v[194:197], v[94:97]
	v_mfma_f32_16x16x32_bf16 v[90:93], v[154:157], v[194:197], v[90:93]
	v_mfma_f32_16x16x32_bf16 v[78:81], v[140:143], v[202:205], v[78:81]
	v_mfma_f32_16x16x32_bf16 v[74:77], v[154:157], v[202:205], v[74:77]
	v_mfma_f32_16x16x32_bf16 v[126:129], v[144:147], v[182:185], v[126:129]
	v_mfma_f32_16x16x32_bf16 v[122:125], v[158:161], v[182:185], v[122:125]
	v_mfma_f32_16x16x32_bf16 v[110:113], v[144:147], v[190:193], v[110:113]
	v_mfma_f32_16x16x32_bf16 v[106:109], v[158:161], v[190:193], v[106:109]
	v_mfma_f32_16x16x32_bf16 v[94:97], v[144:147], v[198:201], v[94:97]
	v_mfma_f32_16x16x32_bf16 v[90:93], v[158:161], v[198:201], v[90:93]
	v_mfma_f32_16x16x32_bf16 v[78:81], v[144:147], v[206:209], v[78:81]
	v_mfma_f32_16x16x32_bf16 v[74:77], v[158:161], v[206:209], v[74:77]
	s_setprio 0
	s_setprio 1
	v_mfma_f32_16x16x32_bf16 v[118:121], v[162:165], v[178:181], v[118:121]
	v_mfma_f32_16x16x32_bf16 v[114:117], v[170:173], v[178:181], v[114:117]
	v_mfma_f32_16x16x32_bf16 v[102:105], v[162:165], v[186:189], v[102:105]
	v_mfma_f32_16x16x32_bf16 v[98:101], v[170:173], v[186:189], v[98:101]
	v_mfma_f32_16x16x32_bf16 v[86:89], v[162:165], v[194:197], v[86:89]
	v_mfma_f32_16x16x32_bf16 v[82:85], v[170:173], v[194:197], v[82:85]
	v_mfma_f32_16x16x32_bf16 v[70:73], v[162:165], v[202:205], v[70:73]
	v_mfma_f32_16x16x32_bf16 v[66:69], v[170:173], v[202:205], v[66:69]
	v_mfma_f32_16x16x32_bf16 v[118:121], v[166:169], v[182:185], v[118:121]
	v_mfma_f32_16x16x32_bf16 v[114:117], v[174:177], v[182:185], v[114:117]
	v_mfma_f32_16x16x32_bf16 v[102:105], v[166:169], v[190:193], v[102:105]
	v_mfma_f32_16x16x32_bf16 v[98:101], v[174:177], v[190:193], v[98:101]
	v_mfma_f32_16x16x32_bf16 v[86:89], v[166:169], v[198:201], v[86:89]
	v_mfma_f32_16x16x32_bf16 v[82:85], v[174:177], v[198:201], v[82:85]
	v_mfma_f32_16x16x32_bf16 v[70:73], v[166:169], v[206:209], v[70:73]
	v_mfma_f32_16x16x32_bf16 v[66:69], v[174:177], v[206:209], v[66:69]
	s_barrier
; #define PG8_STAGE(bufoff, gbase, voff) do { _Pragma("unroll") for (int _i = 0; _i < 2; ++_i) \
;         __builtin_amdgcn_global_load_lds((const unsigned*)((const char*)(gbase) + (voff)[_i]), (PG8_LAS unsigned*)(lds + (bufoff) + ldsw + _i * 8192), 16, 0, 0); } while (0)
; #define PG8_LDA(dst, b, h) do { _Pragma("unroll") for (int m = 0; m < 4; ++m) _Pragma("unroll") for (int k = 0; k < 2; ++k) dst[m][k] = *(const PG8_LAS bf16x8*)(lds + PG8_SA(b, h) + aoff + m * 2048 + k * 1024); } while (0)
; #define PG8_MMA(ai, bj, At, Bt) do { __builtin_amdgcn_s_setprio(1); _Pragma("unroll") for (int m = 0; m < 4; ++m) _Pragma("unroll") for (int n = 0; n < 2; ++n) _Pragma("unroll") for (int k = 0; k < 2; ++k) \
;         acc[ai][bj][m][n] = __builtin_amdgcn_mfma_f32_16x16x32_bf16(Bt[n][k], At[m][k], acc[ai][bj][m][n], 0, 0, 0); __builtin_amdgcn_s_setprio(0); } while (0)
; #define PG8_WAIT_V(n) asm volatile("s_waitcnt vmcnt(" #n ")" ::: "memory")
; #define PG8_WAIT_L(n) asm volatile("s_waitcnt lgkmcnt(" #n ")" ::: "memory")
; #define PG8_BAR __builtin_amdgcn_s_barrier()
; #define PG8_SCHED __builtin_amdgcn_sched_barrier(0)
; template <class Epi, class Sched, bool ALIGN_EPI = false, bool SP2 = false>
; __device__ __forceinline__ void gemm_phase(PG8_LAS unsigned char* lds, const Gemm g, const Sched& S, const Epi& E) {
;     ...
;         for (int t = 0; t < nt; t += 2) {
;             const bool last = (t == nt - 2);
;     ...
;             PG8_WAIT_V(8); PG8_WAIT_L(0); PG8_BAR; PG8_MMA(0, 0, At, B0); PG8_MMA(0, 1, At, B1); PG8_BAR; PG8_SCHED;
;             PG8_LDA(At, 1, 1); PG8_STAGE(PG8_SB(1, 0), b3, voffB); PG8_STAGE(PG8_SB(1, 1), b3 + hstep, voffB); PG8_STAGE(PG8_SA(1, 0), a3, voffA);
;             PG8_WAIT_V(8); PG8_WAIT_L(0); PG8_BAR; PG8_MMA(1, 0, At, B0); PG8_MMA(1, 1, At, B1); PG8_BAR; PG8_SCHED;
	s_setprio 0
	s_add_i32 s21, s21, s1
	v_lshl_add_u64 v[210:211], v[210:211], 0, s[34:35]
	s_mov_b32 m0, s21
	ds_read_b128 v[178:181], v153 offset:49152
	ds_read_b128 v[182:185], v153 offset:50176
	ds_read_b128 v[186:189], v153 offset:51200
	ds_read_b128 v[190:193], v153 offset:52224
	ds_read_b128 v[194:197], v153 offset:53248
	ds_read_b128 v[198:201], v153 offset:54272
	ds_read_b128 v[202:205], v153 offset:55296
	ds_read_b128 v[206:209], v153 offset:56320
	global_load_lds_dwordx4 v[210:211], off
	s_add_i32 m0, s21, 0x2000
	s_add_u32 s10, s10, 0x80080
	v_lshl_add_u64 v[210:211], v[212:213], 0, s[34:35]
	s_addc_u32 s11, s11, 0
	s_add_i32 s21, s62, s1
	global_load_lds_dwordx4 v[210:211], off
	v_lshl_add_u64 v[210:211], s[10:11], 0, v[0:1]
	s_mov_b32 m0, s21
	s_nop 0
	global_load_lds_dwordx4 v[210:211], off
	v_lshl_add_u64 v[210:211], s[10:11], 0, v[134:135]
	s_add_i32 m0, s21, 0x2000
	s_nop 0
	global_load_lds_dwordx4 v[210:211], off
	v_lshl_add_u64 v[210:211], v[214:215], 0, s[34:35]
	s_mov_b32 m0, s7
	s_nop 0
	global_load_lds_dwordx4 v[210:211], off
	v_lshl_add_u64 v[210:211], v[216:217], 0, s[34:35]
	s_mov_b32 m0, s30
	s_nop 0
	global_load_lds_dwordx4 v[210:211], off
	s_waitcnt vmcnt(8)
	s_waitcnt lgkmcnt(0)
	s_setprio 1
	s_barrier
	v_mfma_f32_16x16x32_bf16 v[62:65], v[140:143], v[178:181], v[62:65]
	v_mfma_f32_16x16x32_bf16 v[58:61], v[154:157], v[178:181], v[58:61]
	v_mfma_f32_16x16x32_bf16 v[46:49], v[140:143], v[186:189], v[46:49]
	v_mfma_f32_16x16x32_bf16 v[42:45], v[154:157], v[186:189], v[42:45]
	v_mfma_f32_16x16x32_bf16 v[30:33], v[140:143], v[194:197], v[30:33]
	v_mfma_f32_16x16x32_bf16 v[26:29], v[154:157], v[194:197], v[26:29]
	v_mfma_f32_16x16x32_bf16 v[14:17], v[140:143], v[202:205], v[14:17]
	v_mfma_f32_16x16x32_bf16 v[10:13], v[154:157], v[202:205], v[10:13]
	v_mfma_f32_16x16x32_bf16 v[62:65], v[144:147], v[182:185], v[62:65]
	v_mfma_f32_16x16x32_bf16 v[58:61], v[158:161], v[182:185], v[58:61]
	v_mfma_f32_16x16x32_bf16 v[46:49], v[144:147], v[190:193], v[46:49]
	v_mfma_f32_16x16x32_bf16 v[42:45], v[158:161], v[190:193], v[42:45]
	v_mfma_f32_16x16x32_bf16 v[30:33], v[144:147], v[198:201], v[30:33]
	v_mfma_f32_16x16x32_bf16 v[26:29], v[158:161], v[198:201], v[26:29]
	v_mfma_f32_16x16x32_bf16 v[14:17], v[144:147], v[206:209], v[14:17]
	v_mfma_f32_16x16x32_bf16 v[10:13], v[158:161], v[206:209], v[10:13]
	s_setprio 0
	s_setprio 1
	v_mfma_f32_16x16x32_bf16 v[54:57], v[162:165], v[178:181], v[54:57]
	v_mfma_f32_16x16x32_bf16 v[50:53], v[170:173], v[178:181], v[50:53]
	v_mfma_f32_16x16x32_bf16 v[38:41], v[162:165], v[186:189], v[38:41]
	v_mfma_f32_16x16x32_bf16 v[34:37], v[170:173], v[186:189], v[34:37]
	v_mfma_f32_16x16x32_bf16 v[22:25], v[162:165], v[194:197], v[22:25]
	v_mfma_f32_16x16x32_bf16 v[18:21], v[170:173], v[194:197], v[18:21]
	v_mfma_f32_16x16x32_bf16 v[6:9], v[162:165], v[202:205], v[6:9]
	v_mfma_f32_16x16x32_bf16 v[2:5], v[170:173], v[202:205], v[2:5]
	v_mfma_f32_16x16x32_bf16 v[54:57], v[166:169], v[182:185], v[54:57]
	v_mfma_f32_16x16x32_bf16 v[50:53], v[174:177], v[182:185], v[50:53]
	v_mfma_f32_16x16x32_bf16 v[38:41], v[166:169], v[190:193], v[38:41]
	v_mfma_f32_16x16x32_bf16 v[34:37], v[174:177], v[190:193], v[34:37]
	v_mfma_f32_16x16x32_bf16 v[22:25], v[166:169], v[198:201], v[22:25]
	v_mfma_f32_16x16x32_bf16 v[18:21], v[174:177], v[198:201], v[18:21]
	v_mfma_f32_16x16x32_bf16 v[6:9], v[166:169], v[206:209], v[6:9]
	v_mfma_f32_16x16x32_bf16 v[2:5], v[174:177], v[206:209], v[2:5]
	s_barrier
	s_setprio 0
	s_add_i32 s13, s13, 2
	s_add_u32 s16, s16, 0x100
	s_addc_u32 s17, s17, 0
	s_add_u32 s61, s61, 0x100
	s_addc_u32 s12, s12, 0
	s_cmp_gt_u32 s13, 29
	s_cbranch_scc0 .LBB0_169
	s_and_b64 vcc, exec, s[22:23]
	s_cbranch_vccz .LBB0_172
	s_barrier

; #define PG8_STAGE(bufoff, gbase, voff) do { _Pragma("unroll") for (int _i = 0; _i < 2; ++_i) \
;         __builtin_amdgcn_global_load_lds((const unsigned*)((const char*)(gbase) + (voff)[_i]), (PG8_LAS unsigned*)(lds + (bufoff) + ldsw + _i * 8192), 16, 0, 0); } while (0)
; #define PG8_LDA(dst, b, h) do { _Pragma("unroll") for (int m = 0; m < 4; ++m) _Pragma("unroll") for (int k = 0; k < 2; ++k) dst[m][k] = *(const PG8_LAS bf16x8*)(lds + PG8_SA(b, h) + aoff + m * 2048 + k * 1024); } while (0)
; #define PG8_LDB(dst, b, h) do { _Pragma("unroll") for (int n = 0; n < 2; ++n) _Pragma("unroll") for (int k = 0; k < 2; ++k) dst[n][k] = *(const PG8_LAS bf16x8*)(lds + PG8_SB(b, h) + boff + n * 2048 + k * 1024); } while (0)
; #define PG8_MMA(ai, bj, At, Bt) do { __builtin_amdgcn_s_setprio(1); _Pragma("unroll") for (int m = 0; m < 4; ++m) _Pragma("unroll") for (int n = 0; n < 2; ++n) _Pragma("unroll") for (int k = 0; k < 2; ++k) \
;         acc[ai][bj][m][n] = __builtin_amdgcn_mfma_f32_16x16x32_bf16(Bt[n][k], At[m][k], acc[ai][bj][m][n], 0, 0, 0); __builtin_amdgcn_s_setprio(0); } while (0)
; #define PG8_WAIT_V(n) asm volatile("s_waitcnt vmcnt(" #n ")" ::: "memory")
; #define PG8_WAIT_L(n) asm volatile("s_waitcnt lgkmcnt(" #n ")" ::: "memory")
; #define PG8_BAR __builtin_amdgcn_s_barrier()
; #define PG8_SCHED __builtin_amdgcn_sched_barrier(0)
; template <class Epi, class Sched, bool ALIGN_EPI = false, bool SP2 = false>
; __device__ __forceinline__ void gemm_phase(PG8_LAS unsigned char* lds, const Gemm g, const Sched& S, const Epi& E) {
;     ...
;             if constexpr (SP2) {
;             PG8_LDB(B0, 0, 0); PG8_LDB(B1, 0, 1); PG8_SCHED; PG8_LDA(At, 0, 0); PG8_STAGE(PG8_SA(1, 1), a1 + hstep, voffA);
;             PG8_WAIT_V(8); PG8_WAIT_L(0); PG8_BAR; PG8_MMA(0, 0, At, B0); PG8_MMA(0, 1, At, B1); PG8_BAR; PG8_SCHED;
;             PG8_LDA(At, 0, 1); PG8_STAGE(PG8_SB(0, 0), b2, voffB); PG8_STAGE(PG8_SB(0, 1), b2 + hstep, voffB); PG8_STAGE(PG8_SA(0, 0), a2, voffA);
;             PG8_WAIT_V(8); PG8_WAIT_L(0); PG8_BAR; PG8_MMA(1, 0, At, B0); PG8_MMA(1, 1, At, B1); PG8_BAR; PG8_SCHED;
.LBB0_223:
	s_add_i32 s14, s10, 2
	s_add_u32 s15, s8, 0x80
	s_addc_u32 s11, s9, 0
	s_add_i32 s64, 0, 0x10000
	s_cmp_eq_u32 s57, s10
	s_cselect_b32 s11, s51, s11
	s_cselect_b32 s10, s50, s15
	s_cselect_b32 s45, s53, s13
	s_cselect_b32 s44, s52, s12
	s_add_i32 s15, 0, 0x14000
	v_add_u32_e32 v156, s64, v145
	v_add_u32_e32 v172, s15, v145
	ds_read_b128 v[140:143], v156
	ds_read_b128 v[148:151], v156 offset:1024
	ds_read_b128 v[152:155], v156 offset:2048
	ds_read_b128 v[156:159], v156 offset:3072
	ds_read_b128 v[160:163], v172
	ds_read_b128 v[164:167], v172 offset:1024
	ds_read_b128 v[168:171], v172 offset:2048
	ds_read_b128 v[172:175], v172 offset:3072
	v_lshl_add_u64 v[208:209], s[8:9], 0, v[136:137]
	s_add_i32 m0, s21, 0xc000
	ds_read_b128 v[176:179], v147
	ds_read_b128 v[180:183], v147 offset:1024
	ds_read_b128 v[184:187], v147 offset:2048
	ds_read_b128 v[188:191], v147 offset:3072
	ds_read_b128 v[192:195], v147 offset:4096
	ds_read_b128 v[196:199], v147 offset:5120
	ds_read_b128 v[200:203], v147 offset:6144
	ds_read_b128 v[204:207], v147 offset:7168
	global_load_lds_dwordx4 v[208:209], off
	v_lshl_add_u64 v[208:209], s[8:9], 0, v[138:139]
	s_add_i32 m0, s21, 0xe000
	s_nop 0
	global_load_lds_dwordx4 v[208:209], off
	s_waitcnt vmcnt(8)
	s_waitcnt lgkmcnt(0)
	s_setprio 1
	s_barrier
	v_mfma_f32_16x16x32_bf16 v[126:129], v[140:143], v[176:179], v[126:129]
	v_mfma_f32_16x16x32_bf16 v[122:125], v[152:155], v[176:179], v[122:125]
	v_mfma_f32_16x16x32_bf16 v[110:113], v[140:143], v[184:187], v[110:113]
	v_mfma_f32_16x16x32_bf16 v[106:109], v[152:155], v[184:187], v[106:109]
	v_mfma_f32_16x16x32_bf16 v[94:97], v[140:143], v[192:195], v[94:97]
	v_mfma_f32_16x16x32_bf16 v[90:93], v[152:155], v[192:195], v[90:93]
	v_mfma_f32_16x16x32_bf16 v[78:81], v[140:143], v[200:203], v[78:81]
	v_mfma_f32_16x16x32_bf16 v[74:77], v[152:155], v[200:203], v[74:77]
	v_mfma_f32_16x16x32_bf16 v[126:129], v[148:151], v[180:183], v[126:129]
	v_mfma_f32_16x16x32_bf16 v[122:125], v[156:159], v[180:183], v[122:125]
	v_mfma_f32_16x16x32_bf16 v[110:113], v[148:151], v[188:191], v[110:113]
	v_mfma_f32_16x16x32_bf16 v[106:109], v[156:159], v[188:191], v[106:109]
	v_mfma_f32_16x16x32_bf16 v[94:97], v[148:151], v[196:199], v[94:97]
	v_mfma_f32_16x16x32_bf16 v[90:93], v[156:159], v[196:199], v[90:93]
	v_mfma_f32_16x16x32_bf16 v[78:81], v[148:151], v[204:207], v[78:81]
	v_mfma_f32_16x16x32_bf16 v[74:77], v[156:159], v[204:207], v[74:77]
	s_setprio 0
	s_setprio 1
	v_mfma_f32_16x16x32_bf16 v[118:121], v[160:163], v[176:179], v[118:121]
	v_mfma_f32_16x16x32_bf16 v[114:117], v[168:171], v[176:179], v[114:117]
	v_mfma_f32_16x16x32_bf16 v[102:105], v[160:163], v[184:187], v[102:105]
	v_mfma_f32_16x16x32_bf16 v[98:101], v[168:171], v[184:187], v[98:101]
	v_mfma_f32_16x16x32_bf16 v[86:89], v[160:163], v[192:195], v[86:89]
	v_mfma_f32_16x16x32_bf16 v[82:85], v[168:171], v[192:195], v[82:85]
	v_mfma_f32_16x16x32_bf16 v[70:73], v[160:163], v[200:203], v[70:73]
	v_mfma_f32_16x16x32_bf16 v[66:69], v[168:171], v[200:203], v[66:69]
	v_mfma_f32_16x16x32_bf16 v[118:121], v[164:167], v[180:183], v[118:121]
	v_mfma_f32_16x16x32_bf16 v[114:117], v[172:175], v[180:183], v[114:117]
	v_mfma_f32_16x16x32_bf16 v[102:105], v[164:167], v[188:191], v[102:105]
	v_mfma_f32_16x16x32_bf16 v[98:101], v[172:175], v[188:191], v[98:101]
	v_mfma_f32_16x16x32_bf16 v[86:89], v[164:167], v[196:199], v[86:89]
	v_mfma_f32_16x16x32_bf16 v[82:85], v[172:175], v[196:199], v[82:85]
	v_mfma_f32_16x16x32_bf16 v[70:73], v[164:167], v[204:207], v[70:73]
	v_mfma_f32_16x16x32_bf16 v[66:69], v[172:175], v[204:207], v[66:69]
	s_barrier
	s_setprio 0
	s_add_i32 s64, s64, s7
	v_lshl_add_u64 v[208:209], s[44:45], 0, v[0:1]
	s_mov_b32 m0, s64
	ds_read_b128 v[176:179], v147 offset:16384
	ds_read_b128 v[180:183], v147 offset:17408
	ds_read_b128 v[184:187], v147 offset:18432
	ds_read_b128 v[188:191], v147 offset:19456
	ds_read_b128 v[192:195], v147 offset:20480
	ds_read_b128 v[196:199], v147 offset:21504
	ds_read_b128 v[200:203], v147 offset:22528
	ds_read_b128 v[204:207], v147 offset:23552
	global_load_lds_dwordx4 v[208:209], off
	s_add_i32 m0, s64, 0x2000
	v_lshl_add_u64 v[210:211], s[44:45], 0, v[134:135]
	s_add_u32 s44, s44, s30
	s_addc_u32 s45, s45, 0
	s_add_i32 s15, s15, s7
	global_load_lds_dwordx4 v[210:211], off
	v_lshl_add_u64 v[212:213], s[44:45], 0, v[0:1]
	s_mov_b32 m0, s15
	v_lshl_add_u64 v[214:215], s[44:45], 0, v[134:135]
	global_load_lds_dwordx4 v[212:213], off
	s_add_i32 m0, s15, 0x2000
	v_lshl_add_u64 v[216:217], s[10:11], 0, v[130:131]
	global_load_lds_dwordx4 v[214:215], off
	s_mov_b32 m0, s21
	v_lshl_add_u64 v[222:223], s[10:11], 0, v[132:133]
	global_load_lds_dwordx4 v[216:217], off
	s_mov_b32 m0, s26
	s_nop 0
	global_load_lds_dwordx4 v[222:223], off
	s_waitcnt vmcnt(8)
	s_waitcnt lgkmcnt(0)
	s_setprio 1
	s_barrier
; #define PG8_STAGE(bufoff, gbase, voff) do { _Pragma("unroll") for (int _i = 0; _i < 2; ++_i) \
;         __builtin_amdgcn_global_load_lds((const unsigned*)((const char*)(gbase) + (voff)[_i]), (PG8_LAS unsigned*)(lds + (bufoff) + ldsw + _i * 8192), 16, 0, 0); } while (0)
; #define PG8_LDA(dst, b, h) do { _Pragma("unroll") for (int m = 0; m < 4; ++m) _Pragma("unroll") for (int k = 0; k < 2; ++k) dst[m][k] = *(const PG8_LAS bf16x8*)(lds + PG8_SA(b, h) + aoff + m * 2048 + k * 1024); } while (0)
; #define PG8_LDB(dst, b, h) do { _Pragma("unroll") for (int n = 0; n < 2; ++n) _Pragma("unroll") for (int k = 0; k < 2; ++k) dst[n][k] = *(const PG8_LAS bf16x8*)(lds + PG8_SB(b, h) + boff + n * 2048 + k * 1024); } while (0)
; #define PG8_MMA(ai, bj, At, Bt) do { __builtin_amdgcn_s_setprio(1); _Pragma("unroll") for (int m = 0; m < 4; ++m) _Pragma("unroll") for (int n = 0; n < 2; ++n) _Pragma("unroll") for (int k = 0; k < 2; ++k) \
;         acc[ai][bj][m][n] = __builtin_amdgcn_mfma_f32_16x16x32_bf16(Bt[n][k], At[m][k], acc[ai][bj][m][n], 0, 0, 0); __builtin_amdgcn_s_setprio(0); } while (0)
; #define PG8_WAIT_V(n) asm volatile("s_waitcnt vmcnt(" #n ")" ::: "memory")
; #define PG8_WAIT_L(n) asm volatile("s_waitcnt lgkmcnt(" #n ")" ::: "memory")
; #define PG8_BAR __builtin_amdgcn_s_barrier()
; #define PG8_SCHED __builtin_amdgcn_sched_barrier(0)
; template <class Epi, class Sched, bool ALIGN_EPI = false, bool SP2 = false>
; __device__ __forceinline__ void gemm_phase(PG8_LAS unsigned char* lds, const Gemm g, const Sched& S, const Epi& E) {
;     ...
;             PG8_LDA(At, 0, 1); PG8_STAGE(PG8_SB(0, 0), b2, voffB); PG8_STAGE(PG8_SB(0, 1), b2 + hstep, voffB); PG8_STAGE(PG8_SA(0, 0), a2, voffA);
;             PG8_WAIT_V(8); PG8_WAIT_L(0); PG8_BAR; PG8_MMA(1, 0, At, B0); PG8_MMA(1, 1, At, B1); PG8_BAR; PG8_SCHED;
;             PG8_LDB(B0, 1, 0); PG8_LDB(B1, 1, 1); PG8_SCHED; PG8_LDA(At, 1, 0); PG8_STAGE(PG8_SA(0, 1), a2 + hstep, voffA);
;             PG8_WAIT_V(8); PG8_WAIT_L(0); PG8_BAR; PG8_MMA(0, 0, At, B0); PG8_MMA(0, 1, At, B1); PG8_BAR; PG8_SCHED;
	v_mfma_f32_16x16x32_bf16 v[62:65], v[140:143], v[176:179], v[62:65]
	v_mfma_f32_16x16x32_bf16 v[58:61], v[152:155], v[176:179], v[58:61]
	v_mfma_f32_16x16x32_bf16 v[46:49], v[140:143], v[184:187], v[46:49]
	v_mfma_f32_16x16x32_bf16 v[42:45], v[152:155], v[184:187], v[42:45]
	v_mfma_f32_16x16x32_bf16 v[30:33], v[140:143], v[192:195], v[30:33]
	v_mfma_f32_16x16x32_bf16 v[26:29], v[152:155], v[192:195], v[26:29]
	v_mfma_f32_16x16x32_bf16 v[14:17], v[140:143], v[200:203], v[14:17]
	v_mfma_f32_16x16x32_bf16 v[10:13], v[152:155], v[200:203], v[10:13]
	v_mfma_f32_16x16x32_bf16 v[62:65], v[148:151], v[180:183], v[62:65]
	v_mfma_f32_16x16x32_bf16 v[58:61], v[156:159], v[180:183], v[58:61]
	v_mfma_f32_16x16x32_bf16 v[46:49], v[148:151], v[188:191], v[46:49]
	v_mfma_f32_16x16x32_bf16 v[42:45], v[156:159], v[188:191], v[42:45]
	v_mfma_f32_16x16x32_bf16 v[30:33], v[148:151], v[196:199], v[30:33]
	v_mfma_f32_16x16x32_bf16 v[26:29], v[156:159], v[196:199], v[26:29]
	v_mfma_f32_16x16x32_bf16 v[14:17], v[148:151], v[204:207], v[14:17]
	v_mfma_f32_16x16x32_bf16 v[10:13], v[156:159], v[204:207], v[10:13]
	s_setprio 0
	s_setprio 1
	v_mfma_f32_16x16x32_bf16 v[54:57], v[160:163], v[176:179], v[54:57]
	v_mfma_f32_16x16x32_bf16 v[50:53], v[168:171], v[176:179], v[50:53]
	v_mfma_f32_16x16x32_bf16 v[38:41], v[160:163], v[184:187], v[38:41]
	v_mfma_f32_16x16x32_bf16 v[34:37], v[168:171], v[184:187], v[34:37]
	v_mfma_f32_16x16x32_bf16 v[22:25], v[160:163], v[192:195], v[22:25]
	v_mfma_f32_16x16x32_bf16 v[18:21], v[168:171], v[192:195], v[18:21]
	v_mfma_f32_16x16x32_bf16 v[6:9], v[160:163], v[200:203], v[6:9]
	v_mfma_f32_16x16x32_bf16 v[2:5], v[168:171], v[200:203], v[2:5]
	v_mfma_f32_16x16x32_bf16 v[54:57], v[164:167], v[180:183], v[54:57]
	v_mfma_f32_16x16x32_bf16 v[50:53], v[172:175], v[180:183], v[50:53]
	v_mfma_f32_16x16x32_bf16 v[38:41], v[164:167], v[188:191], v[38:41]
	v_mfma_f32_16x16x32_bf16 v[34:37], v[172:175], v[188:191], v[34:37]
	v_mfma_f32_16x16x32_bf16 v[22:25], v[164:167], v[196:199], v[22:25]
	v_mfma_f32_16x16x32_bf16 v[18:21], v[172:175], v[196:199], v[18:21]
	v_mfma_f32_16x16x32_bf16 v[6:9], v[164:167], v[204:207], v[6:9]
	v_mfma_f32_16x16x32_bf16 v[2:5], v[172:175], v[204:207], v[2:5]
	s_barrier
	s_setprio 0
	s_add_i32 s15, 0, 0x18000
	s_add_i32 s44, 0, 0x1c000
	v_add_u32_e32 v156, s15, v145
	v_add_u32_e32 v172, s44, v145
	ds_read_b128 v[140:143], v156
	ds_read_b128 v[148:151], v156 offset:1024
	ds_read_b128 v[152:155], v156 offset:2048
	ds_read_b128 v[156:159], v156 offset:3072
	ds_read_b128 v[160:163], v172
	ds_read_b128 v[164:167], v172 offset:1024
	ds_read_b128 v[168:171], v172 offset:2048
	ds_read_b128 v[172:175], v172 offset:3072
	s_add_u32 s10, s10, s30
	s_addc_u32 s11, s11, 0
	s_mov_b32 m0, s27
	v_lshl_add_u64 v[224:225], s[10:11], 0, v[130:131]
	ds_read_b128 v[176:179], v147 offset:32768
	ds_read_b128 v[180:183], v147 offset:33792
	ds_read_b128 v[184:187], v147 offset:34816
	ds_read_b128 v[188:191], v147 offset:35840
	ds_read_b128 v[192:195], v147 offset:36864
	ds_read_b128 v[196:199], v147 offset:37888
	ds_read_b128 v[200:203], v147 offset:38912
	ds_read_b128 v[204:207], v147 offset:39936
	global_load_lds_dwordx4 v[224:225], off
	v_lshl_add_u64 v[224:225], s[10:11], 0, v[132:133]
	s_mov_b32 m0, s54
	s_nop 0
	global_load_lds_dwordx4 v[224:225], off
	s_waitcnt vmcnt(8)
	s_waitcnt lgkmcnt(0)
	s_setprio 1
	s_barrier
	v_mfma_f32_16x16x32_bf16 v[126:129], v[140:143], v[176:179], v[126:129]
	v_mfma_f32_16x16x32_bf16 v[122:125], v[152:155], v[176:179], v[122:125]
	v_mfma_f32_16x16x32_bf16 v[110:113], v[140:143], v[184:187], v[110:113]
	v_mfma_f32_16x16x32_bf16 v[106:109], v[152:155], v[184:187], v[106:109]
	v_mfma_f32_16x16x32_bf16 v[94:97], v[140:143], v[192:195], v[94:97]
	v_mfma_f32_16x16x32_bf16 v[90:93], v[152:155], v[192:195], v[90:93]
	v_mfma_f32_16x16x32_bf16 v[78:81], v[140:143], v[200:203], v[78:81]
	v_mfma_f32_16x16x32_bf16 v[74:77], v[152:155], v[200:203], v[74:77]
	v_mfma_f32_16x16x32_bf16 v[126:129], v[148:151], v[180:183], v[126:129]
	v_mfma_f32_16x16x32_bf16 v[122:125], v[156:159], v[180:183], v[122:125]
	v_mfma_f32_16x16x32_bf16 v[110:113], v[148:151], v[188:191], v[110:113]
	v_mfma_f32_16x16x32_bf16 v[106:109], v[156:159], v[188:191], v[106:109]
	v_mfma_f32_16x16x32_bf16 v[94:97], v[148:151], v[196:199], v[94:97]
	v_mfma_f32_16x16x32_bf16 v[90:93], v[156:159], v[196:199], v[90:93]
	v_mfma_f32_16x16x32_bf16 v[78:81], v[148:151], v[204:207], v[78:81]
	v_mfma_f32_16x16x32_bf16 v[74:77], v[156:159], v[204:207], v[74:77]
	s_setprio 0
	s_setprio 1
	v_mfma_f32_16x16x32_bf16 v[118:121], v[160:163], v[176:179], v[118:121]
	v_mfma_f32_16x16x32_bf16 v[114:117], v[168:171], v[176:179], v[114:117]
	v_mfma_f32_16x16x32_bf16 v[102:105], v[160:163], v[184:187], v[102:105]
	v_mfma_f32_16x16x32_bf16 v[98:101], v[168:171], v[184:187], v[98:101]
	v_mfma_f32_16x16x32_bf16 v[86:89], v[160:163], v[192:195], v[86:89]
	v_mfma_f32_16x16x32_bf16 v[82:85], v[168:171], v[192:195], v[82:85]
	v_mfma_f32_16x16x32_bf16 v[70:73], v[160:163], v[200:203], v[70:73]
	v_mfma_f32_16x16x32_bf16 v[66:69], v[168:171], v[200:203], v[66:69]
	v_mfma_f32_16x16x32_bf16 v[118:121], v[164:167], v[180:183], v[118:121]
	v_mfma_f32_16x16x32_bf16 v[114:117], v[172:175], v[180:183], v[114:117]
	v_mfma_f32_16x16x32_bf16 v[102:105], v[164:167], v[188:191], v[102:105]
	v_mfma_f32_16x16x32_bf16 v[98:101], v[172:175], v[188:191], v[98:101]
	v_mfma_f32_16x16x32_bf16 v[86:89], v[164:167], v[196:199], v[86:89]
	v_mfma_f32_16x16x32_bf16 v[82:85], v[172:175], v[196:199], v[82:85]
	v_mfma_f32_16x16x32_bf16 v[70:73], v[164:167], v[204:207], v[70:73]
	v_mfma_f32_16x16x32_bf16 v[66:69], v[172:175], v[204:207], v[66:69]
	s_barrier
; #define PG8_STAGE(bufoff, gbase, voff) do { _Pragma("unroll") for (int _i = 0; _i < 2; ++_i) \
;         __builtin_amdgcn_global_load_lds((const unsigned*)((const char*)(gbase) + (voff)[_i]), (PG8_LAS unsigned*)(lds + (bufoff) + ldsw + _i * 8192), 16, 0, 0); } while (0)
; #define PG8_LDA(dst, b, h) do { _Pragma("unroll") for (int m = 0; m < 4; ++m) _Pragma("unroll") for (int k = 0; k < 2; ++k) dst[m][k] = *(const PG8_LAS bf16x8*)(lds + PG8_SA(b, h) + aoff + m * 2048 + k * 1024); } while (0)
; #define PG8_MMA(ai, bj, At, Bt) do { __builtin_amdgcn_s_setprio(1); _Pragma("unroll") for (int m = 0; m < 4; ++m) _Pragma("unroll") for (int n = 0; n < 2; ++n) _Pragma("unroll") for (int k = 0; k < 2; ++k) \
;         acc[ai][bj][m][n] = __builtin_amdgcn_mfma_f32_16x16x32_bf16(Bt[n][k], At[m][k], acc[ai][bj][m][n], 0, 0, 0); __builtin_amdgcn_s_setprio(0); } while (0)
; #define PG8_WAIT_V(n) asm volatile("s_waitcnt vmcnt(" #n ")" ::: "memory")
; #define PG8_WAIT_L(n) asm volatile("s_waitcnt lgkmcnt(" #n ")" ::: "memory")
; #define PG8_BAR __builtin_amdgcn_s_barrier()
; #define PG8_SCHED __builtin_amdgcn_sched_barrier(0)
; template <class Epi, class Sched, bool ALIGN_EPI = false, bool SP2 = false>
; __device__ __forceinline__ void gemm_phase(PG8_LAS unsigned char* lds, const Gemm g, const Sched& S, const Epi& E) {
;     ...
;             PG8_LDA(At, 1, 1); PG8_STAGE(PG8_SB(1, 0), b3, voffB); PG8_STAGE(PG8_SB(1, 1), b3 + hstep, voffB); PG8_STAGE(PG8_SA(1, 0), a3, voffA);
;             PG8_WAIT_V(8); PG8_WAIT_L(0); PG8_BAR; PG8_MMA(1, 0, At, B0); PG8_MMA(1, 1, At, B1); PG8_BAR; PG8_SCHED;
	s_setprio 0
	s_add_i32 s10, s15, s7
	v_lshl_add_u64 v[208:209], v[208:209], 0, s[34:35]
	s_mov_b32 m0, s10
	ds_read_b128 v[176:179], v147 offset:49152
	ds_read_b128 v[180:183], v147 offset:50176
	ds_read_b128 v[184:187], v147 offset:51200
	ds_read_b128 v[188:191], v147 offset:52224
	ds_read_b128 v[192:195], v147 offset:53248
	ds_read_b128 v[196:199], v147 offset:54272
	ds_read_b128 v[200:203], v147 offset:55296
	ds_read_b128 v[204:207], v147 offset:56320
	global_load_lds_dwordx4 v[208:209], off
	v_lshl_add_u64 v[208:209], v[210:211], 0, s[34:35]
	s_add_i32 m0, s10, 0x2000
	s_add_i32 s10, s44, s7
	global_load_lds_dwordx4 v[208:209], off
	v_lshl_add_u64 v[208:209], v[212:213], 0, s[34:35]
	s_mov_b32 m0, s10
	s_nop 0
	global_load_lds_dwordx4 v[208:209], off
	v_lshl_add_u64 v[208:209], v[214:215], 0, s[34:35]
	s_add_i32 m0, s10, 0x2000
	s_nop 0
	global_load_lds_dwordx4 v[208:209], off
	v_lshl_add_u64 v[208:209], v[216:217], 0, s[34:35]
	s_mov_b32 m0, s16
	s_nop 0
	global_load_lds_dwordx4 v[208:209], off
	v_lshl_add_u64 v[208:209], v[222:223], 0, s[34:35]
	s_mov_b32 m0, s17
	s_nop 0
	global_load_lds_dwordx4 v[208:209], off
	s_waitcnt vmcnt(8)
	s_waitcnt lgkmcnt(0)
	s_setprio 1
	s_barrier
	v_mfma_f32_16x16x32_bf16 v[62:65], v[140:143], v[176:179], v[62:65]
	v_mfma_f32_16x16x32_bf16 v[58:61], v[152:155], v[176:179], v[58:61]
	v_mfma_f32_16x16x32_bf16 v[46:49], v[140:143], v[184:187], v[46:49]
	v_mfma_f32_16x16x32_bf16 v[42:45], v[152:155], v[184:187], v[42:45]
	v_mfma_f32_16x16x32_bf16 v[30:33], v[140:143], v[192:195], v[30:33]
	v_mfma_f32_16x16x32_bf16 v[26:29], v[152:155], v[192:195], v[26:29]
	v_mfma_f32_16x16x32_bf16 v[14:17], v[140:143], v[200:203], v[14:17]
	v_mfma_f32_16x16x32_bf16 v[10:13], v[152:155], v[200:203], v[10:13]
	v_mfma_f32_16x16x32_bf16 v[62:65], v[148:151], v[180:183], v[62:65]
	v_mfma_f32_16x16x32_bf16 v[58:61], v[156:159], v[180:183], v[58:61]
	v_mfma_f32_16x16x32_bf16 v[46:49], v[148:151], v[188:191], v[46:49]
	v_mfma_f32_16x16x32_bf16 v[42:45], v[156:159], v[188:191], v[42:45]
	v_mfma_f32_16x16x32_bf16 v[30:33], v[148:151], v[196:199], v[30:33]
	v_mfma_f32_16x16x32_bf16 v[26:29], v[156:159], v[196:199], v[26:29]
	v_mfma_f32_16x16x32_bf16 v[14:17], v[148:151], v[204:207], v[14:17]
	v_mfma_f32_16x16x32_bf16 v[10:13], v[156:159], v[204:207], v[10:13]
	s_setprio 0
	s_setprio 1
	v_mfma_f32_16x16x32_bf16 v[54:57], v[160:163], v[176:179], v[54:57]
	v_mfma_f32_16x16x32_bf16 v[50:53], v[168:171], v[176:179], v[50:53]
	v_mfma_f32_16x16x32_bf16 v[38:41], v[160:163], v[184:187], v[38:41]
	v_mfma_f32_16x16x32_bf16 v[34:37], v[168:171], v[184:187], v[34:37]
	v_mfma_f32_16x16x32_bf16 v[22:25], v[160:163], v[192:195], v[22:25]
	v_mfma_f32_16x16x32_bf16 v[18:21], v[168:171], v[192:195], v[18:21]
	v_mfma_f32_16x16x32_bf16 v[6:9], v[160:163], v[200:203], v[6:9]
	v_mfma_f32_16x16x32_bf16 v[2:5], v[168:171], v[200:203], v[2:5]
	v_mfma_f32_16x16x32_bf16 v[54:57], v[164:167], v[180:183], v[54:57]
	v_mfma_f32_16x16x32_bf16 v[50:53], v[172:175], v[180:183], v[50:53]
	v_mfma_f32_16x16x32_bf16 v[38:41], v[164:167], v[188:191], v[38:41]
	v_mfma_f32_16x16x32_bf16 v[34:37], v[172:175], v[188:191], v[34:37]
	v_mfma_f32_16x16x32_bf16 v[22:25], v[164:167], v[196:199], v[22:25]
	v_mfma_f32_16x16x32_bf16 v[18:21], v[172:175], v[196:199], v[18:21]
	v_mfma_f32_16x16x32_bf16 v[6:9], v[164:167], v[204:207], v[6:9]
	v_mfma_f32_16x16x32_bf16 v[2:5], v[172:175], v[204:207], v[2:5]
	s_barrier
	s_setprio 0
	s_add_u32 s8, s8, 0x100
	s_addc_u32 s9, s9, 0
	s_add_u32 s12, s12, 0x100
	s_addc_u32 s13, s13, 0
	s_cmp_ge_u32 s14, s56
	s_mov_b32 s10, s14
	s_cbranch_scc0 .LBB0_223
	s_and_b64 vcc, exec, s[46:47]
	s_cbranch_vccz .LBB0_226
	s_barrier

; #define PG8_STAGE(bufoff, gbase, voff) do { _Pragma("unroll") for (int _i = 0; _i < 2; ++_i) \
;         __builtin_amdgcn_global_load_lds((const unsigned*)((const char*)(gbase) + (voff)[_i]), (PG8_LAS unsigned*)(lds + (bufoff) + ldsw + _i * 8192), 16, 0, 0); } while (0)
; #define PG8_LDA(dst, b, h) do { _Pragma("unroll") for (int m = 0; m < 4; ++m) _Pragma("unroll") for (int k = 0; k < 2; ++k) dst[m][k] = *(const PG8_LAS bf16x8*)(lds + PG8_SA(b, h) + aoff + m * 2048 + k * 1024); } while (0)
; #define PG8_LDB(dst, b, h) do { _Pragma("unroll") for (int n = 0; n < 2; ++n) _Pragma("unroll") for (int k = 0; k < 2; ++k) dst[n][k] = *(const PG8_LAS bf16x8*)(lds + PG8_SB(b, h) + boff + n * 2048 + k * 1024); } while (0)
; #define PG8_MMA(ai, bj, At, Bt) do { __builtin_amdgcn_s_setprio(1); _Pragma("unroll") for (int m = 0; m < 4; ++m) _Pragma("unroll") for (int n = 0; n < 2; ++n) _Pragma("unroll") for (int k = 0; k < 2; ++k) \
;         acc[ai][bj][m][n] = __builtin_amdgcn_mfma_f32_16x16x32_bf16(Bt[n][k], At[m][k], acc[ai][bj][m][n], 0, 0, 0); __builtin_amdgcn_s_setprio(0); } while (0)
; #define PG8_WAIT_V(n) asm volatile("s_waitcnt vmcnt(" #n ")" ::: "memory")
; #define PG8_WAIT_L(n) asm volatile("s_waitcnt lgkmcnt(" #n ")" ::: "memory")
; #define PG8_BAR __builtin_amdgcn_s_barrier()
; #define PG8_SCHED __builtin_amdgcn_sched_barrier(0)
; template <class Epi, class Sched, bool ALIGN_EPI = false, bool SP2 = false>
; __device__ __forceinline__ void gemm_phase(PG8_LAS unsigned char* lds, const Gemm g, const Sched& S, const Epi& E) {
;     ...
;             PG8_LDB(B0, 0, 0); PG8_LDB(B1, 0, 1); PG8_SCHED; PG8_LDA(At, 0, 0); PG8_STAGE(PG8_SA(1, 1), a1 + hstep, voffA);
;             PG8_WAIT_V(8); PG8_WAIT_L(0); PG8_BAR; PG8_MMA(0, 0, At, B0); PG8_MMA(0, 1, At, B1); PG8_BAR; PG8_SCHED;
;             PG8_LDA(At, 0, 1); PG8_STAGE(PG8_SB(0, 0), b2, voffB); PG8_STAGE(PG8_SB(0, 1), b2 + hstep, voffB); PG8_STAGE(PG8_SA(0, 0), a2, voffA);
.LBB0_559:
	s_add_u32 s10, s50, 0xfff80080
	s_addc_u32 s11, s51, -1
	s_add_i32 s60, 0, 0x10000
	s_cmp_eq_u32 s59, 28
	s_cselect_b32 s53, s37, s11
	s_cselect_b32 s52, s43, s10
	v_add_u32_e32 v144, s60, v149
	s_cselect_b32 s11, s23, s58
	s_cselect_b32 s10, s56, s57
	s_add_i32 s62, 0, 0x14000
	ds_read_b128 v[140:143], v144
	ds_read_b128 v[152:155], v144 offset:1024
	ds_read_b128 v[156:159], v144 offset:2048
	ds_read_b128 v[160:163], v144 offset:3072
	v_add_u32_e32 v144, s62, v149
	ds_read_b128 v[164:167], v144
	ds_read_b128 v[168:171], v144 offset:1024
	ds_read_b128 v[172:175], v144 offset:2048
	ds_read_b128 v[176:179], v144 offset:3072
	v_lshl_add_u64 v[144:145], s[50:51], 0, v[136:137]
	s_add_i32 m0, s5, 0xc000
	ds_read_b128 v[180:183], v151
	ds_read_b128 v[184:187], v151 offset:1024
	ds_read_b128 v[188:191], v151 offset:2048
	ds_read_b128 v[192:195], v151 offset:3072
	ds_read_b128 v[196:199], v151 offset:4096
	ds_read_b128 v[200:203], v151 offset:5120
	ds_read_b128 v[204:207], v151 offset:6144
	ds_read_b128 v[208:211], v151 offset:7168
	global_load_lds_dwordx4 v[144:145], off
	v_lshl_add_u64 v[144:145], s[50:51], 0, v[138:139]
	s_add_i32 m0, s5, 0xe000
	s_nop 0
	global_load_lds_dwordx4 v[144:145], off
	s_waitcnt vmcnt(8)
	s_waitcnt lgkmcnt(0)
	s_setprio 1
	s_barrier
	v_mfma_f32_16x16x32_bf16 v[126:129], v[140:143], v[180:183], v[126:129]
	v_mfma_f32_16x16x32_bf16 v[122:125], v[156:159], v[180:183], v[122:125]
	v_mfma_f32_16x16x32_bf16 v[110:113], v[140:143], v[188:191], v[110:113]
	v_mfma_f32_16x16x32_bf16 v[106:109], v[156:159], v[188:191], v[106:109]
	v_mfma_f32_16x16x32_bf16 v[94:97], v[140:143], v[196:199], v[94:97]
	v_mfma_f32_16x16x32_bf16 v[90:93], v[156:159], v[196:199], v[90:93]
	v_mfma_f32_16x16x32_bf16 v[78:81], v[140:143], v[204:207], v[78:81]
	v_mfma_f32_16x16x32_bf16 v[74:77], v[156:159], v[204:207], v[74:77]
	v_mfma_f32_16x16x32_bf16 v[126:129], v[152:155], v[184:187], v[126:129]
	v_mfma_f32_16x16x32_bf16 v[122:125], v[160:163], v[184:187], v[122:125]
	v_mfma_f32_16x16x32_bf16 v[110:113], v[152:155], v[192:195], v[110:113]
	v_mfma_f32_16x16x32_bf16 v[106:109], v[160:163], v[192:195], v[106:109]
	v_mfma_f32_16x16x32_bf16 v[94:97], v[152:155], v[200:203], v[94:97]
	v_mfma_f32_16x16x32_bf16 v[90:93], v[160:163], v[200:203], v[90:93]
	v_mfma_f32_16x16x32_bf16 v[78:81], v[152:155], v[208:211], v[78:81]
	v_mfma_f32_16x16x32_bf16 v[74:77], v[160:163], v[208:211], v[74:77]
	s_setprio 0
	s_setprio 1
	v_mfma_f32_16x16x32_bf16 v[118:121], v[164:167], v[180:183], v[118:121]
	v_mfma_f32_16x16x32_bf16 v[114:117], v[172:175], v[180:183], v[114:117]
	v_mfma_f32_16x16x32_bf16 v[102:105], v[164:167], v[188:191], v[102:105]
	v_mfma_f32_16x16x32_bf16 v[98:101], v[172:175], v[188:191], v[98:101]
	v_mfma_f32_16x16x32_bf16 v[86:89], v[164:167], v[196:199], v[86:89]
	v_mfma_f32_16x16x32_bf16 v[82:85], v[172:175], v[196:199], v[82:85]
	v_mfma_f32_16x16x32_bf16 v[70:73], v[164:167], v[204:207], v[70:73]
	v_mfma_f32_16x16x32_bf16 v[66:69], v[172:175], v[204:207], v[66:69]
	v_mfma_f32_16x16x32_bf16 v[118:121], v[168:171], v[184:187], v[118:121]
	v_mfma_f32_16x16x32_bf16 v[114:117], v[176:179], v[184:187], v[114:117]
	v_mfma_f32_16x16x32_bf16 v[102:105], v[168:171], v[192:195], v[102:105]
	v_mfma_f32_16x16x32_bf16 v[98:101], v[176:179], v[192:195], v[98:101]
	v_mfma_f32_16x16x32_bf16 v[86:89], v[168:171], v[200:203], v[86:89]
	v_mfma_f32_16x16x32_bf16 v[82:85], v[176:179], v[200:203], v[82:85]
	v_mfma_f32_16x16x32_bf16 v[70:73], v[168:171], v[208:211], v[70:73]
	v_mfma_f32_16x16x32_bf16 v[66:69], v[176:179], v[208:211], v[66:69]
	s_barrier
	s_setprio 0
	s_add_i32 s60, s60, s4
	v_lshl_add_u64 v[144:145], s[10:11], 0, v[0:1]
	s_mov_b32 m0, s60
	ds_read_b128 v[180:183], v151 offset:16384
	ds_read_b128 v[184:187], v151 offset:17408
	ds_read_b128 v[188:191], v151 offset:18432
	ds_read_b128 v[192:195], v151 offset:19456
	ds_read_b128 v[196:199], v151 offset:20480
	ds_read_b128 v[200:203], v151 offset:21504
	ds_read_b128 v[204:207], v151 offset:22528
	ds_read_b128 v[208:211], v151 offset:23552
	global_load_lds_dwordx4 v[144:145], off
	s_add_i32 m0, s60, 0x2000
	s_add_u32 s60, s10, 0x80000
	v_lshl_add_u64 v[212:213], s[10:11], 0, v[134:135]
	s_addc_u32 s61, s11, 0
	s_add_i32 s62, s62, s4
	global_load_lds_dwordx4 v[212:213], off
	v_lshl_add_u64 v[214:215], s[60:61], 0, v[0:1]
	s_mov_b32 m0, s62
	v_lshl_add_u64 v[216:217], s[52:53], 0, v[132:133]
	global_load_lds_dwordx4 v[214:215], off
	v_lshl_add_u64 v[214:215], s[60:61], 0, v[134:135]
	s_add_i32 m0, s62, 0x2000
	s_nop 0
	global_load_lds_dwordx4 v[214:215], off
	v_lshl_add_u64 v[214:215], s[52:53], 0, v[130:131]
	s_mov_b32 m0, s5
	s_nop 0
	global_load_lds_dwordx4 v[214:215], off
	s_mov_b32 m0, s6
	s_nop 0
	global_load_lds_dwordx4 v[216:217], off
	s_waitcnt vmcnt(8)
	s_waitcnt lgkmcnt(0)
	s_setprio 1
	s_barrier
; #define PG8_STAGE(bufoff, gbase, voff) do { _Pragma("unroll") for (int _i = 0; _i < 2; ++_i) \
;         __builtin_amdgcn_global_load_lds((const unsigned*)((const char*)(gbase) + (voff)[_i]), (PG8_LAS unsigned*)(lds + (bufoff) + ldsw + _i * 8192), 16, 0, 0); } while (0)
; #define PG8_LDA(dst, b, h) do { _Pragma("unroll") for (int m = 0; m < 4; ++m) _Pragma("unroll") for (int k = 0; k < 2; ++k) dst[m][k] = *(const PG8_LAS bf16x8*)(lds + PG8_SA(b, h) + aoff + m * 2048 + k * 1024); } while (0)
; #define PG8_LDB(dst, b, h) do { _Pragma("unroll") for (int n = 0; n < 2; ++n) _Pragma("unroll") for (int k = 0; k < 2; ++k) dst[n][k] = *(const PG8_LAS bf16x8*)(lds + PG8_SB(b, h) + boff + n * 2048 + k * 1024); } while (0)
; #define PG8_MMA(ai, bj, At, Bt) do { __builtin_amdgcn_s_setprio(1); _Pragma("unroll") for (int m = 0; m < 4; ++m) _Pragma("unroll") for (int n = 0; n < 2; ++n) _Pragma("unroll") for (int k = 0; k < 2; ++k) \
;         acc[ai][bj][m][n] = __builtin_amdgcn_mfma_f32_16x16x32_bf16(Bt[n][k], At[m][k], acc[ai][bj][m][n], 0, 0, 0); __builtin_amdgcn_s_setprio(0); } while (0)
; #define PG8_WAIT_V(n) asm volatile("s_waitcnt vmcnt(" #n ")" ::: "memory")
; #define PG8_WAIT_L(n) asm volatile("s_waitcnt lgkmcnt(" #n ")" ::: "memory")
; #define PG8_BAR __builtin_amdgcn_s_barrier()
; #define PG8_SCHED __builtin_amdgcn_sched_barrier(0)
; template <class Epi, class Sched, bool ALIGN_EPI = false, bool SP2 = false>
; __device__ __forceinline__ void gemm_phase(PG8_LAS unsigned char* lds, const Gemm g, const Sched& S, const Epi& E) {
;     ...
;             PG8_WAIT_V(8); PG8_WAIT_L(0); PG8_BAR; PG8_MMA(1, 0, At, B0); PG8_MMA(1, 1, At, B1); PG8_BAR; PG8_SCHED;
;             PG8_LDB(B0, 1, 0); PG8_LDB(B1, 1, 1); PG8_SCHED; PG8_LDA(At, 1, 0); PG8_STAGE(PG8_SA(0, 1), a2 + hstep, voffA);
;             PG8_WAIT_V(8); PG8_WAIT_L(0); PG8_BAR; PG8_MMA(0, 0, At, B0); PG8_MMA(0, 1, At, B1); PG8_BAR; PG8_SCHED;
	v_mfma_f32_16x16x32_bf16 v[62:65], v[140:143], v[180:183], v[62:65]
	v_mfma_f32_16x16x32_bf16 v[58:61], v[156:159], v[180:183], v[58:61]
	v_mfma_f32_16x16x32_bf16 v[46:49], v[140:143], v[188:191], v[46:49]
	v_mfma_f32_16x16x32_bf16 v[42:45], v[156:159], v[188:191], v[42:45]
	v_mfma_f32_16x16x32_bf16 v[30:33], v[140:143], v[196:199], v[30:33]
	v_mfma_f32_16x16x32_bf16 v[26:29], v[156:159], v[196:199], v[26:29]
	v_mfma_f32_16x16x32_bf16 v[14:17], v[140:143], v[204:207], v[14:17]
	v_mfma_f32_16x16x32_bf16 v[10:13], v[156:159], v[204:207], v[10:13]
	v_mfma_f32_16x16x32_bf16 v[62:65], v[152:155], v[184:187], v[62:65]
	v_mfma_f32_16x16x32_bf16 v[58:61], v[160:163], v[184:187], v[58:61]
	v_mfma_f32_16x16x32_bf16 v[46:49], v[152:155], v[192:195], v[46:49]
	v_mfma_f32_16x16x32_bf16 v[42:45], v[160:163], v[192:195], v[42:45]
	v_mfma_f32_16x16x32_bf16 v[30:33], v[152:155], v[200:203], v[30:33]
	v_mfma_f32_16x16x32_bf16 v[26:29], v[160:163], v[200:203], v[26:29]
	v_mfma_f32_16x16x32_bf16 v[14:17], v[152:155], v[208:211], v[14:17]
	v_mfma_f32_16x16x32_bf16 v[10:13], v[160:163], v[208:211], v[10:13]
	s_setprio 0
	s_setprio 1
	v_mfma_f32_16x16x32_bf16 v[54:57], v[164:167], v[180:183], v[54:57]
	v_mfma_f32_16x16x32_bf16 v[50:53], v[172:175], v[180:183], v[50:53]
	v_mfma_f32_16x16x32_bf16 v[38:41], v[164:167], v[188:191], v[38:41]
	v_mfma_f32_16x16x32_bf16 v[34:37], v[172:175], v[188:191], v[34:37]
	v_mfma_f32_16x16x32_bf16 v[22:25], v[164:167], v[196:199], v[22:25]
	v_mfma_f32_16x16x32_bf16 v[18:21], v[172:175], v[196:199], v[18:21]
	v_mfma_f32_16x16x32_bf16 v[6:9], v[164:167], v[204:207], v[6:9]
	v_mfma_f32_16x16x32_bf16 v[2:5], v[172:175], v[204:207], v[2:5]
	v_mfma_f32_16x16x32_bf16 v[54:57], v[168:171], v[184:187], v[54:57]
	v_mfma_f32_16x16x32_bf16 v[50:53], v[176:179], v[184:187], v[50:53]
	v_mfma_f32_16x16x32_bf16 v[38:41], v[168:171], v[192:195], v[38:41]
	v_mfma_f32_16x16x32_bf16 v[34:37], v[176:179], v[192:195], v[34:37]
	v_mfma_f32_16x16x32_bf16 v[22:25], v[168:171], v[200:203], v[22:25]
	v_mfma_f32_16x16x32_bf16 v[18:21], v[176:179], v[200:203], v[18:21]
	v_mfma_f32_16x16x32_bf16 v[6:9], v[168:171], v[208:211], v[6:9]
	v_mfma_f32_16x16x32_bf16 v[2:5], v[176:179], v[208:211], v[2:5]
	s_barrier
	s_setprio 0
	s_add_i32 s60, 0, 0x18000
	v_add_u32_e32 v146, s60, v149
	s_add_i32 s61, 0, 0x1c000
	ds_read_b128 v[140:143], v146
	ds_read_b128 v[152:155], v146 offset:1024
	ds_read_b128 v[156:159], v146 offset:2048
	ds_read_b128 v[160:163], v146 offset:3072
	v_add_u32_e32 v146, s61, v149
	ds_read_b128 v[164:167], v146
	ds_read_b128 v[168:171], v146 offset:1024
	ds_read_b128 v[172:175], v146 offset:2048
	ds_read_b128 v[176:179], v146 offset:3072
	s_add_u32 s52, s52, 0x80000
	s_addc_u32 s53, s53, 0
	s_mov_b32 m0, s7
	v_lshl_add_u64 v[222:223], s[52:53], 0, v[130:131]
	ds_read_b128 v[180:183], v151 offset:32768
	ds_read_b128 v[184:187], v151 offset:33792
	ds_read_b128 v[188:191], v151 offset:34816
	ds_read_b128 v[192:195], v151 offset:35840
	ds_read_b128 v[196:199], v151 offset:36864
	ds_read_b128 v[200:203], v151 offset:37888
	ds_read_b128 v[204:207], v151 offset:38912
	ds_read_b128 v[208:211], v151 offset:39936
	global_load_lds_dwordx4 v[222:223], off
	v_lshl_add_u64 v[222:223], s[52:53], 0, v[132:133]
	s_mov_b32 m0, s17
	s_nop 0
	global_load_lds_dwordx4 v[222:223], off
	s_waitcnt vmcnt(8)
	s_waitcnt lgkmcnt(0)
	s_setprio 1
	s_barrier
	v_mfma_f32_16x16x32_bf16 v[126:129], v[140:143], v[180:183], v[126:129]
	v_mfma_f32_16x16x32_bf16 v[122:125], v[156:159], v[180:183], v[122:125]
	v_mfma_f32_16x16x32_bf16 v[110:113], v[140:143], v[188:191], v[110:113]
	v_mfma_f32_16x16x32_bf16 v[106:109], v[156:159], v[188:191], v[106:109]
	v_mfma_f32_16x16x32_bf16 v[94:97], v[140:143], v[196:199], v[94:97]
	v_mfma_f32_16x16x32_bf16 v[90:93], v[156:159], v[196:199], v[90:93]
	v_mfma_f32_16x16x32_bf16 v[78:81], v[140:143], v[204:207], v[78:81]
	v_mfma_f32_16x16x32_bf16 v[74:77], v[156:159], v[204:207], v[74:77]
	v_mfma_f32_16x16x32_bf16 v[126:129], v[152:155], v[184:187], v[126:129]
	v_mfma_f32_16x16x32_bf16 v[122:125], v[160:163], v[184:187], v[122:125]
	v_mfma_f32_16x16x32_bf16 v[110:113], v[152:155], v[192:195], v[110:113]
	v_mfma_f32_16x16x32_bf16 v[106:109], v[160:163], v[192:195], v[106:109]
	v_mfma_f32_16x16x32_bf16 v[94:97], v[152:155], v[200:203], v[94:97]
	v_mfma_f32_16x16x32_bf16 v[90:93], v[160:163], v[200:203], v[90:93]
	v_mfma_f32_16x16x32_bf16 v[78:81], v[152:155], v[208:211], v[78:81]
	v_mfma_f32_16x16x32_bf16 v[74:77], v[160:163], v[208:211], v[74:77]
	s_setprio 0
	s_setprio 1
	v_mfma_f32_16x16x32_bf16 v[118:121], v[164:167], v[180:183], v[118:121]
	v_mfma_f32_16x16x32_bf16 v[114:117], v[172:175], v[180:183], v[114:117]
	v_mfma_f32_16x16x32_bf16 v[102:105], v[164:167], v[188:191], v[102:105]
	v_mfma_f32_16x16x32_bf16 v[98:101], v[172:175], v[188:191], v[98:101]
	v_mfma_f32_16x16x32_bf16 v[86:89], v[164:167], v[196:199], v[86:89]
	v_mfma_f32_16x16x32_bf16 v[82:85], v[172:175], v[196:199], v[82:85]
	v_mfma_f32_16x16x32_bf16 v[70:73], v[164:167], v[204:207], v[70:73]
	v_mfma_f32_16x16x32_bf16 v[66:69], v[172:175], v[204:207], v[66:69]
	v_mfma_f32_16x16x32_bf16 v[118:121], v[168:171], v[184:187], v[118:121]
	v_mfma_f32_16x16x32_bf16 v[114:117], v[176:179], v[184:187], v[114:117]
	v_mfma_f32_16x16x32_bf16 v[102:105], v[168:171], v[192:195], v[102:105]
	v_mfma_f32_16x16x32_bf16 v[98:101], v[176:179], v[192:195], v[98:101]
	v_mfma_f32_16x16x32_bf16 v[86:89], v[168:171], v[200:203], v[86:89]
	v_mfma_f32_16x16x32_bf16 v[82:85], v[176:179], v[200:203], v[82:85]
	v_mfma_f32_16x16x32_bf16 v[70:73], v[168:171], v[208:211], v[70:73]
	v_mfma_f32_16x16x32_bf16 v[66:69], v[176:179], v[208:211], v[66:69]
	s_barrier
; #define PG8_STAGE(bufoff, gbase, voff) do { _Pragma("unroll") for (int _i = 0; _i < 2; ++_i) \
;         __builtin_amdgcn_global_load_lds((const unsigned*)((const char*)(gbase) + (voff)[_i]), (PG8_LAS unsigned*)(lds + (bufoff) + ldsw + _i * 8192), 16, 0, 0); } while (0)
; #define PG8_LDA(dst, b, h) do { _Pragma("unroll") for (int m = 0; m < 4; ++m) _Pragma("unroll") for (int k = 0; k < 2; ++k) dst[m][k] = *(const PG8_LAS bf16x8*)(lds + PG8_SA(b, h) + aoff + m * 2048 + k * 1024); } while (0)
; #define PG8_MMA(ai, bj, At, Bt) do { __builtin_amdgcn_s_setprio(1); _Pragma("unroll") for (int m = 0; m < 4; ++m) _Pragma("unroll") for (int n = 0; n < 2; ++n) _Pragma("unroll") for (int k = 0; k < 2; ++k) \
;         acc[ai][bj][m][n] = __builtin_amdgcn_mfma_f32_16x16x32_bf16(Bt[n][k], At[m][k], acc[ai][bj][m][n], 0, 0, 0); __builtin_amdgcn_s_setprio(0); } while (0)
; #define PG8_WAIT_V(n) asm volatile("s_waitcnt vmcnt(" #n ")" ::: "memory")
; #define PG8_WAIT_L(n) asm volatile("s_waitcnt lgkmcnt(" #n ")" ::: "memory")
; #define PG8_BAR __builtin_amdgcn_s_barrier()
; #define PG8_SCHED __builtin_amdgcn_sched_barrier(0)
; template <class Epi, class Sched, bool ALIGN_EPI = false, bool SP2 = false>
; __device__ __forceinline__ void gemm_phase(PG8_LAS unsigned char* lds, const Gemm g, const Sched& S, const Epi& E) {
;     ...
;         for (int t = 0; t < nt; t += 2) {
;             const bool last = (t == nt - 2);
;             const char* a1 = cA + (size_t)(t + 1) * kstep;
;             const char* a2 = last ? nA : cA + (size_t)(t + 2) * kstep; const char* b2 = last ? nB : cB + (size_t)(t + 2) * kstep;
;             const char* a3 = a2 + kstep; const char* b3 = b2 + kstep;
;     ...
;             PG8_LDA(At, 1, 1); PG8_STAGE(PG8_SB(1, 0), b3, voffB); PG8_STAGE(PG8_SB(1, 1), b3 + hstep, voffB); PG8_STAGE(PG8_SA(1, 0), a3, voffA);
;             PG8_WAIT_V(8); PG8_WAIT_L(0); PG8_BAR; PG8_MMA(1, 0, At, B0); PG8_MMA(1, 1, At, B1); PG8_BAR; PG8_SCHED;
	s_setprio 0
	s_add_i32 s52, s60, s4
	v_lshl_add_u64 v[144:145], v[144:145], 0, s[34:35]
	s_mov_b32 m0, s52
	ds_read_b128 v[180:183], v151 offset:49152
	ds_read_b128 v[184:187], v151 offset:50176
	ds_read_b128 v[188:191], v151 offset:51200
	ds_read_b128 v[192:195], v151 offset:52224
	ds_read_b128 v[196:199], v151 offset:53248
	ds_read_b128 v[200:203], v151 offset:54272
	ds_read_b128 v[204:207], v151 offset:55296
	ds_read_b128 v[208:211], v151 offset:56320
	global_load_lds_dwordx4 v[144:145], off
	s_add_i32 m0, s52, 0x2000
	s_add_u32 s10, s10, 0x80080
	v_lshl_add_u64 v[144:145], v[212:213], 0, s[34:35]
	s_addc_u32 s11, s11, 0
	s_add_i32 s52, s61, s4
	global_load_lds_dwordx4 v[144:145], off
	v_lshl_add_u64 v[144:145], s[10:11], 0, v[0:1]
	s_mov_b32 m0, s52
	s_nop 0
	global_load_lds_dwordx4 v[144:145], off
	v_lshl_add_u64 v[144:145], s[10:11], 0, v[134:135]
	s_add_i32 m0, s52, 0x2000
	s_nop 0
	global_load_lds_dwordx4 v[144:145], off
	v_lshl_add_u64 v[144:145], v[214:215], 0, s[34:35]
	s_mov_b32 m0, s30
	s_nop 0
	global_load_lds_dwordx4 v[144:145], off
	v_lshl_add_u64 v[144:145], v[216:217], 0, s[34:35]
	s_mov_b32 m0, s47
	s_nop 0
	global_load_lds_dwordx4 v[144:145], off
	s_waitcnt vmcnt(8)
	s_waitcnt lgkmcnt(0)
	s_setprio 1
	s_barrier
	v_mfma_f32_16x16x32_bf16 v[62:65], v[140:143], v[180:183], v[62:65]
	v_mfma_f32_16x16x32_bf16 v[58:61], v[156:159], v[180:183], v[58:61]
	v_mfma_f32_16x16x32_bf16 v[46:49], v[140:143], v[188:191], v[46:49]
	v_mfma_f32_16x16x32_bf16 v[42:45], v[156:159], v[188:191], v[42:45]
	v_mfma_f32_16x16x32_bf16 v[30:33], v[140:143], v[196:199], v[30:33]
	v_mfma_f32_16x16x32_bf16 v[26:29], v[156:159], v[196:199], v[26:29]
	v_mfma_f32_16x16x32_bf16 v[14:17], v[140:143], v[204:207], v[14:17]
	v_mfma_f32_16x16x32_bf16 v[10:13], v[156:159], v[204:207], v[10:13]
	v_mfma_f32_16x16x32_bf16 v[62:65], v[152:155], v[184:187], v[62:65]
	v_mfma_f32_16x16x32_bf16 v[58:61], v[160:163], v[184:187], v[58:61]
	v_mfma_f32_16x16x32_bf16 v[46:49], v[152:155], v[192:195], v[46:49]
	v_mfma_f32_16x16x32_bf16 v[42:45], v[160:163], v[192:195], v[42:45]
	v_mfma_f32_16x16x32_bf16 v[30:33], v[152:155], v[200:203], v[30:33]
	v_mfma_f32_16x16x32_bf16 v[26:29], v[160:163], v[200:203], v[26:29]
	v_mfma_f32_16x16x32_bf16 v[14:17], v[152:155], v[208:211], v[14:17]
	v_mfma_f32_16x16x32_bf16 v[10:13], v[160:163], v[208:211], v[10:13]
	s_setprio 0
	s_setprio 1
	v_mfma_f32_16x16x32_bf16 v[54:57], v[164:167], v[180:183], v[54:57]
	v_mfma_f32_16x16x32_bf16 v[50:53], v[172:175], v[180:183], v[50:53]
	v_mfma_f32_16x16x32_bf16 v[38:41], v[164:167], v[188:191], v[38:41]
	v_mfma_f32_16x16x32_bf16 v[34:37], v[172:175], v[188:191], v[34:37]
	v_mfma_f32_16x16x32_bf16 v[22:25], v[164:167], v[196:199], v[22:25]
	v_mfma_f32_16x16x32_bf16 v[18:21], v[172:175], v[196:199], v[18:21]
	v_mfma_f32_16x16x32_bf16 v[6:9], v[164:167], v[204:207], v[6:9]
	v_mfma_f32_16x16x32_bf16 v[2:5], v[172:175], v[204:207], v[2:5]
	v_mfma_f32_16x16x32_bf16 v[54:57], v[168:171], v[184:187], v[54:57]
	v_mfma_f32_16x16x32_bf16 v[50:53], v[176:179], v[184:187], v[50:53]
	v_mfma_f32_16x16x32_bf16 v[38:41], v[168:171], v[192:195], v[38:41]
	v_mfma_f32_16x16x32_bf16 v[34:37], v[176:179], v[192:195], v[34:37]
	v_mfma_f32_16x16x32_bf16 v[22:25], v[168:171], v[200:203], v[22:25]
	v_mfma_f32_16x16x32_bf16 v[18:21], v[176:179], v[200:203], v[18:21]
	v_mfma_f32_16x16x32_bf16 v[6:9], v[168:171], v[208:211], v[6:9]
	v_mfma_f32_16x16x32_bf16 v[2:5], v[176:179], v[208:211], v[2:5]
	s_barrier
	s_setprio 0
	s_add_i32 s59, s59, 2
	s_add_u32 s50, s50, 0x100
	s_addc_u32 s51, s51, 0
	s_add_u32 s57, s57, 0x100
	s_addc_u32 s58, s58, 0
	s_cmp_gt_u32 s59, 29
	s_cbranch_scc0 .LBB0_559
	s_and_b64 vcc, exec, s[14:15]
	s_cbranch_vccz .LBB0_562
	s_barrier

; #define PG8_STAGE(bufoff, gbase, voff) do { _Pragma("unroll") for (int _i = 0; _i < 2; ++_i) \
;         __builtin_amdgcn_global_load_lds((const unsigned*)((const char*)(gbase) + (voff)[_i]), (PG8_LAS unsigned*)(lds + (bufoff) + ldsw + _i * 8192), 16, 0, 0); } while (0)
; #define PG8_LDA(dst, b, h) do { _Pragma("unroll") for (int m = 0; m < 4; ++m) _Pragma("unroll") for (int k = 0; k < 2; ++k) dst[m][k] = *(const PG8_LAS bf16x8*)(lds + PG8_SA(b, h) + aoff + m * 2048 + k * 1024); } while (0)
; #define PG8_LDB(dst, b, h) do { _Pragma("unroll") for (int n = 0; n < 2; ++n) _Pragma("unroll") for (int k = 0; k < 2; ++k) dst[n][k] = *(const PG8_LAS bf16x8*)(lds + PG8_SB(b, h) + boff + n * 2048 + k * 1024); } while (0)
; #define PG8_MMA(ai, bj, At, Bt) do { __builtin_amdgcn_s_setprio(1); _Pragma("unroll") for (int m = 0; m < 4; ++m) _Pragma("unroll") for (int n = 0; n < 2; ++n) _Pragma("unroll") for (int k = 0; k < 2; ++k) \
;         acc[ai][bj][m][n] = __builtin_amdgcn_mfma_f32_16x16x32_bf16(Bt[n][k], At[m][k], acc[ai][bj][m][n], 0, 0, 0); __builtin_amdgcn_s_setprio(0); } while (0)
; #define PG8_WAIT_V(n) asm volatile("s_waitcnt vmcnt(" #n ")" ::: "memory")
; #define PG8_WAIT_L(n) asm volatile("s_waitcnt lgkmcnt(" #n ")" ::: "memory")
; #define PG8_BAR __builtin_amdgcn_s_barrier()
; #define PG8_SCHED __builtin_amdgcn_sched_barrier(0)
; template <class Epi, class Sched, bool ALIGN_EPI = false, bool SP2 = false>
; __device__ __forceinline__ void gemm_phase(PG8_LAS unsigned char* lds, const Gemm g, const Sched& S, const Epi& E) {
;     ...
;             PG8_LDB(B0, 0, 0); PG8_LDB(B1, 0, 1); PG8_SCHED; PG8_LDA(At, 0, 0); PG8_STAGE(PG8_SA(1, 1), a1 + hstep, voffA);
;             PG8_WAIT_V(8); PG8_WAIT_L(0); PG8_BAR; PG8_MMA(0, 0, At, B0); PG8_MMA(0, 1, At, B1); PG8_BAR; PG8_SCHED;
;             PG8_LDA(At, 0, 1); PG8_STAGE(PG8_SB(0, 0), b2, voffB); PG8_STAGE(PG8_SB(0, 1), b2 + hstep, voffB); PG8_STAGE(PG8_SA(0, 0), a2, voffA);
.LBB0_599:
	s_add_u32 s10, s36, 0xfff80080
	s_addc_u32 s11, s37, -1
	s_add_i32 s55, 0, 0x10000
	s_cmp_eq_u32 s54, 28
	s_cselect_b32 s41, s19, s11
	s_cselect_b32 s40, s50, s10
	v_add_u32_e32 v140, s55, v143
	s_cselect_b32 s11, s17, s53
	s_cselect_b32 s10, s51, s52
	s_add_i32 s58, 0, 0x14000
	ds_read_b128 v[146:149], v140
	ds_read_b128 v[150:153], v140 offset:1024
	ds_read_b128 v[154:157], v140 offset:2048
	ds_read_b128 v[158:161], v140 offset:3072
	v_add_u32_e32 v140, s58, v143
	ds_read_b128 v[162:165], v140
	ds_read_b128 v[166:169], v140 offset:1024
	ds_read_b128 v[170:173], v140 offset:2048
	ds_read_b128 v[174:177], v140 offset:3072
	v_lshl_add_u64 v[140:141], s[36:37], 0, v[136:137]
	s_add_i32 m0, s7, 0xc000
	ds_read_b128 v[178:181], v145
	ds_read_b128 v[182:185], v145 offset:1024
	ds_read_b128 v[186:189], v145 offset:2048
	ds_read_b128 v[190:193], v145 offset:3072
	ds_read_b128 v[194:197], v145 offset:4096
	ds_read_b128 v[198:201], v145 offset:5120
	ds_read_b128 v[202:205], v145 offset:6144
	ds_read_b128 v[206:209], v145 offset:7168
	global_load_lds_dwordx4 v[140:141], off
	v_lshl_add_u64 v[140:141], s[36:37], 0, v[138:139]
	s_add_i32 m0, s7, 0xe000
	s_nop 0
	global_load_lds_dwordx4 v[140:141], off
	s_waitcnt vmcnt(8)
	s_waitcnt lgkmcnt(0)
	s_setprio 1
	s_barrier
	v_mfma_f32_16x16x32_bf16 v[126:129], v[146:149], v[178:181], v[126:129]
	v_mfma_f32_16x16x32_bf16 v[122:125], v[154:157], v[178:181], v[122:125]
	v_mfma_f32_16x16x32_bf16 v[118:121], v[146:149], v[186:189], v[118:121]
	v_mfma_f32_16x16x32_bf16 v[110:113], v[154:157], v[186:189], v[110:113]
	v_mfma_f32_16x16x32_bf16 v[102:105], v[146:149], v[194:197], v[102:105]
	v_mfma_f32_16x16x32_bf16 v[94:97], v[154:157], v[194:197], v[94:97]
	v_mfma_f32_16x16x32_bf16 v[86:89], v[146:149], v[202:205], v[86:89]
	v_mfma_f32_16x16x32_bf16 v[78:81], v[154:157], v[202:205], v[78:81]
	v_mfma_f32_16x16x32_bf16 v[126:129], v[150:153], v[182:185], v[126:129]
	v_mfma_f32_16x16x32_bf16 v[122:125], v[158:161], v[182:185], v[122:125]
	v_mfma_f32_16x16x32_bf16 v[118:121], v[150:153], v[190:193], v[118:121]
	v_mfma_f32_16x16x32_bf16 v[110:113], v[158:161], v[190:193], v[110:113]
	v_mfma_f32_16x16x32_bf16 v[102:105], v[150:153], v[198:201], v[102:105]
	v_mfma_f32_16x16x32_bf16 v[94:97], v[158:161], v[198:201], v[94:97]
	v_mfma_f32_16x16x32_bf16 v[86:89], v[150:153], v[206:209], v[86:89]
	v_mfma_f32_16x16x32_bf16 v[78:81], v[158:161], v[206:209], v[78:81]
	s_setprio 0
	s_setprio 1
	v_mfma_f32_16x16x32_bf16 v[114:117], v[162:165], v[178:181], v[114:117]
	v_mfma_f32_16x16x32_bf16 v[106:109], v[170:173], v[178:181], v[106:109]
	v_mfma_f32_16x16x32_bf16 v[98:101], v[162:165], v[186:189], v[98:101]
	v_mfma_f32_16x16x32_bf16 v[90:93], v[170:173], v[186:189], v[90:93]
	v_mfma_f32_16x16x32_bf16 v[82:85], v[162:165], v[194:197], v[82:85]
	v_mfma_f32_16x16x32_bf16 v[74:77], v[170:173], v[194:197], v[74:77]
	v_mfma_f32_16x16x32_bf16 v[70:73], v[162:165], v[202:205], v[70:73]
	v_mfma_f32_16x16x32_bf16 v[66:69], v[170:173], v[202:205], v[66:69]
	v_mfma_f32_16x16x32_bf16 v[114:117], v[166:169], v[182:185], v[114:117]
	v_mfma_f32_16x16x32_bf16 v[106:109], v[174:177], v[182:185], v[106:109]
	v_mfma_f32_16x16x32_bf16 v[98:101], v[166:169], v[190:193], v[98:101]
	v_mfma_f32_16x16x32_bf16 v[90:93], v[174:177], v[190:193], v[90:93]
	v_mfma_f32_16x16x32_bf16 v[82:85], v[166:169], v[198:201], v[82:85]
	v_mfma_f32_16x16x32_bf16 v[74:77], v[174:177], v[198:201], v[74:77]
	v_mfma_f32_16x16x32_bf16 v[70:73], v[166:169], v[206:209], v[70:73]
	v_mfma_f32_16x16x32_bf16 v[66:69], v[174:177], v[206:209], v[66:69]
	s_barrier
	s_setprio 0
	s_add_i32 s55, s55, s4
	v_lshl_add_u64 v[140:141], s[10:11], 0, v[0:1]
	s_mov_b32 m0, s55
	ds_read_b128 v[178:181], v145 offset:16384
	ds_read_b128 v[182:185], v145 offset:17408
	ds_read_b128 v[186:189], v145 offset:18432
	ds_read_b128 v[190:193], v145 offset:19456
	ds_read_b128 v[194:197], v145 offset:20480
	ds_read_b128 v[198:201], v145 offset:21504
	ds_read_b128 v[202:205], v145 offset:22528
	ds_read_b128 v[206:209], v145 offset:23552
	global_load_lds_dwordx4 v[140:141], off
	s_add_i32 m0, s55, 0x2000
	s_add_u32 s56, s10, 0x80000
	v_lshl_add_u64 v[210:211], s[10:11], 0, v[134:135]
	s_addc_u32 s57, s11, 0
	s_add_i32 s55, s58, s4
	global_load_lds_dwordx4 v[210:211], off
	v_lshl_add_u64 v[212:213], s[56:57], 0, v[0:1]
	s_mov_b32 m0, s55
	v_lshl_add_u64 v[214:215], s[40:41], 0, v[132:133]
	global_load_lds_dwordx4 v[212:213], off
	v_lshl_add_u64 v[212:213], s[56:57], 0, v[134:135]
	s_add_i32 m0, s55, 0x2000
	s_nop 0
	global_load_lds_dwordx4 v[212:213], off
	v_lshl_add_u64 v[212:213], s[40:41], 0, v[130:131]
	s_mov_b32 m0, s7
	s_nop 0
	global_load_lds_dwordx4 v[212:213], off
	s_mov_b32 m0, s21
	s_nop 0
	global_load_lds_dwordx4 v[214:215], off
	s_waitcnt vmcnt(8)
	s_waitcnt lgkmcnt(0)
	s_setprio 1
	s_barrier
; #define PG8_STAGE(bufoff, gbase, voff) do { _Pragma("unroll") for (int _i = 0; _i < 2; ++_i) \
;         __builtin_amdgcn_global_load_lds((const unsigned*)((const char*)(gbase) + (voff)[_i]), (PG8_LAS unsigned*)(lds + (bufoff) + ldsw + _i * 8192), 16, 0, 0); } while (0)
; #define PG8_LDA(dst, b, h) do { _Pragma("unroll") for (int m = 0; m < 4; ++m) _Pragma("unroll") for (int k = 0; k < 2; ++k) dst[m][k] = *(const PG8_LAS bf16x8*)(lds + PG8_SA(b, h) + aoff + m * 2048 + k * 1024); } while (0)
; #define PG8_LDB(dst, b, h) do { _Pragma("unroll") for (int n = 0; n < 2; ++n) _Pragma("unroll") for (int k = 0; k < 2; ++k) dst[n][k] = *(const PG8_LAS bf16x8*)(lds + PG8_SB(b, h) + boff + n * 2048 + k * 1024); } while (0)
; #define PG8_MMA(ai, bj, At, Bt) do { __builtin_amdgcn_s_setprio(1); _Pragma("unroll") for (int m = 0; m < 4; ++m) _Pragma("unroll") for (int n = 0; n < 2; ++n) _Pragma("unroll") for (int k = 0; k < 2; ++k) \
;         acc[ai][bj][m][n] = __builtin_amdgcn_mfma_f32_16x16x32_bf16(Bt[n][k], At[m][k], acc[ai][bj][m][n], 0, 0, 0); __builtin_amdgcn_s_setprio(0); } while (0)
; #define PG8_WAIT_V(n) asm volatile("s_waitcnt vmcnt(" #n ")" ::: "memory")
; #define PG8_WAIT_L(n) asm volatile("s_waitcnt lgkmcnt(" #n ")" ::: "memory")
; #define PG8_BAR __builtin_amdgcn_s_barrier()
; #define PG8_SCHED __builtin_amdgcn_sched_barrier(0)
; template <class Epi, class Sched, bool ALIGN_EPI = false, bool SP2 = false>
; __device__ __forceinline__ void gemm_phase(PG8_LAS unsigned char* lds, const Gemm g, const Sched& S, const Epi& E) {
;     ...
;             PG8_WAIT_V(8); PG8_WAIT_L(0); PG8_BAR; PG8_MMA(1, 0, At, B0); PG8_MMA(1, 1, At, B1); PG8_BAR; PG8_SCHED;
;             PG8_LDB(B0, 1, 0); PG8_LDB(B1, 1, 1); PG8_SCHED; PG8_LDA(At, 1, 0); PG8_STAGE(PG8_SA(0, 1), a2 + hstep, voffA);
;             PG8_WAIT_V(8); PG8_WAIT_L(0); PG8_BAR; PG8_MMA(0, 0, At, B0); PG8_MMA(0, 1, At, B1); PG8_BAR; PG8_SCHED;
	v_mfma_f32_16x16x32_bf16 v[62:65], v[146:149], v[178:181], v[62:65]
	v_mfma_f32_16x16x32_bf16 v[58:61], v[154:157], v[178:181], v[58:61]
	v_mfma_f32_16x16x32_bf16 v[54:57], v[146:149], v[186:189], v[54:57]
	v_mfma_f32_16x16x32_bf16 v[46:49], v[154:157], v[186:189], v[46:49]
	v_mfma_f32_16x16x32_bf16 v[38:41], v[146:149], v[194:197], v[38:41]
	v_mfma_f32_16x16x32_bf16 v[30:33], v[154:157], v[194:197], v[30:33]
	v_mfma_f32_16x16x32_bf16 v[22:25], v[146:149], v[202:205], v[22:25]
	v_mfma_f32_16x16x32_bf16 v[14:17], v[154:157], v[202:205], v[14:17]
	v_mfma_f32_16x16x32_bf16 v[62:65], v[150:153], v[182:185], v[62:65]
	v_mfma_f32_16x16x32_bf16 v[58:61], v[158:161], v[182:185], v[58:61]
	v_mfma_f32_16x16x32_bf16 v[54:57], v[150:153], v[190:193], v[54:57]
	v_mfma_f32_16x16x32_bf16 v[46:49], v[158:161], v[190:193], v[46:49]
	v_mfma_f32_16x16x32_bf16 v[38:41], v[150:153], v[198:201], v[38:41]
	v_mfma_f32_16x16x32_bf16 v[30:33], v[158:161], v[198:201], v[30:33]
	v_mfma_f32_16x16x32_bf16 v[22:25], v[150:153], v[206:209], v[22:25]
	v_mfma_f32_16x16x32_bf16 v[14:17], v[158:161], v[206:209], v[14:17]
	s_setprio 0
	s_setprio 1
	v_mfma_f32_16x16x32_bf16 v[50:53], v[162:165], v[178:181], v[50:53]
	v_mfma_f32_16x16x32_bf16 v[42:45], v[170:173], v[178:181], v[42:45]
	v_mfma_f32_16x16x32_bf16 v[34:37], v[162:165], v[186:189], v[34:37]
	v_mfma_f32_16x16x32_bf16 v[26:29], v[170:173], v[186:189], v[26:29]
	v_mfma_f32_16x16x32_bf16 v[18:21], v[162:165], v[194:197], v[18:21]
	v_mfma_f32_16x16x32_bf16 v[10:13], v[170:173], v[194:197], v[10:13]
	v_mfma_f32_16x16x32_bf16 v[6:9], v[162:165], v[202:205], v[6:9]
	v_mfma_f32_16x16x32_bf16 v[2:5], v[170:173], v[202:205], v[2:5]
	v_mfma_f32_16x16x32_bf16 v[50:53], v[166:169], v[182:185], v[50:53]
	v_mfma_f32_16x16x32_bf16 v[42:45], v[174:177], v[182:185], v[42:45]
	v_mfma_f32_16x16x32_bf16 v[34:37], v[166:169], v[190:193], v[34:37]
	v_mfma_f32_16x16x32_bf16 v[26:29], v[174:177], v[190:193], v[26:29]
	v_mfma_f32_16x16x32_bf16 v[18:21], v[166:169], v[198:201], v[18:21]
	v_mfma_f32_16x16x32_bf16 v[10:13], v[174:177], v[198:201], v[10:13]
	v_mfma_f32_16x16x32_bf16 v[6:9], v[166:169], v[206:209], v[6:9]
	v_mfma_f32_16x16x32_bf16 v[2:5], v[174:177], v[206:209], v[2:5]
	s_barrier
	s_setprio 0
	s_add_i32 s55, 0, 0x18000
	s_add_i32 s56, 0, 0x1c000
	v_add_u32_e32 v158, s55, v143
	v_add_u32_e32 v174, s56, v143
	ds_read_b128 v[146:149], v158
	ds_read_b128 v[150:153], v158 offset:1024
	ds_read_b128 v[154:157], v158 offset:2048
	ds_read_b128 v[158:161], v158 offset:3072
	ds_read_b128 v[162:165], v174
	ds_read_b128 v[166:169], v174 offset:1024
	ds_read_b128 v[170:173], v174 offset:2048
	ds_read_b128 v[174:177], v174 offset:3072
	s_add_u32 s40, s40, 0x80000
	s_addc_u32 s41, s41, 0
	s_mov_b32 m0, s30
	v_lshl_add_u64 v[216:217], s[40:41], 0, v[130:131]
	ds_read_b128 v[178:181], v145 offset:32768
	ds_read_b128 v[182:185], v145 offset:33792
	ds_read_b128 v[186:189], v145 offset:34816
	ds_read_b128 v[190:193], v145 offset:35840
	ds_read_b128 v[194:197], v145 offset:36864
	ds_read_b128 v[198:201], v145 offset:37888
	ds_read_b128 v[202:205], v145 offset:38912
	ds_read_b128 v[206:209], v145 offset:39936
	global_load_lds_dwordx4 v[216:217], off
	v_lshl_add_u64 v[216:217], s[40:41], 0, v[132:133]
	s_mov_b32 m0, s42
	s_nop 0
	global_load_lds_dwordx4 v[216:217], off
	s_waitcnt vmcnt(8)
	s_waitcnt lgkmcnt(0)
	s_setprio 1
	s_barrier
	v_mfma_f32_16x16x32_bf16 v[126:129], v[146:149], v[178:181], v[126:129]
	v_mfma_f32_16x16x32_bf16 v[122:125], v[154:157], v[178:181], v[122:125]
	v_mfma_f32_16x16x32_bf16 v[118:121], v[146:149], v[186:189], v[118:121]
	v_mfma_f32_16x16x32_bf16 v[110:113], v[154:157], v[186:189], v[110:113]
	v_mfma_f32_16x16x32_bf16 v[102:105], v[146:149], v[194:197], v[102:105]
	v_mfma_f32_16x16x32_bf16 v[94:97], v[154:157], v[194:197], v[94:97]
	v_mfma_f32_16x16x32_bf16 v[86:89], v[146:149], v[202:205], v[86:89]
	v_mfma_f32_16x16x32_bf16 v[78:81], v[154:157], v[202:205], v[78:81]
	v_mfma_f32_16x16x32_bf16 v[126:129], v[150:153], v[182:185], v[126:129]
	v_mfma_f32_16x16x32_bf16 v[122:125], v[158:161], v[182:185], v[122:125]
	v_mfma_f32_16x16x32_bf16 v[118:121], v[150:153], v[190:193], v[118:121]
	v_mfma_f32_16x16x32_bf16 v[110:113], v[158:161], v[190:193], v[110:113]
	v_mfma_f32_16x16x32_bf16 v[102:105], v[150:153], v[198:201], v[102:105]
	v_mfma_f32_16x16x32_bf16 v[94:97], v[158:161], v[198:201], v[94:97]
	v_mfma_f32_16x16x32_bf16 v[86:89], v[150:153], v[206:209], v[86:89]
	v_mfma_f32_16x16x32_bf16 v[78:81], v[158:161], v[206:209], v[78:81]
	s_setprio 0
	s_setprio 1
	v_mfma_f32_16x16x32_bf16 v[114:117], v[162:165], v[178:181], v[114:117]
	v_mfma_f32_16x16x32_bf16 v[106:109], v[170:173], v[178:181], v[106:109]
	v_mfma_f32_16x16x32_bf16 v[98:101], v[162:165], v[186:189], v[98:101]
	v_mfma_f32_16x16x32_bf16 v[90:93], v[170:173], v[186:189], v[90:93]
	v_mfma_f32_16x16x32_bf16 v[82:85], v[162:165], v[194:197], v[82:85]
	v_mfma_f32_16x16x32_bf16 v[74:77], v[170:173], v[194:197], v[74:77]
	v_mfma_f32_16x16x32_bf16 v[70:73], v[162:165], v[202:205], v[70:73]
	v_mfma_f32_16x16x32_bf16 v[66:69], v[170:173], v[202:205], v[66:69]
	v_mfma_f32_16x16x32_bf16 v[114:117], v[166:169], v[182:185], v[114:117]
	v_mfma_f32_16x16x32_bf16 v[106:109], v[174:177], v[182:185], v[106:109]
	v_mfma_f32_16x16x32_bf16 v[98:101], v[166:169], v[190:193], v[98:101]
	v_mfma_f32_16x16x32_bf16 v[90:93], v[174:177], v[190:193], v[90:93]
	v_mfma_f32_16x16x32_bf16 v[82:85], v[166:169], v[198:201], v[82:85]
	v_mfma_f32_16x16x32_bf16 v[74:77], v[174:177], v[198:201], v[74:77]
	v_mfma_f32_16x16x32_bf16 v[70:73], v[166:169], v[206:209], v[70:73]
	v_mfma_f32_16x16x32_bf16 v[66:69], v[174:177], v[206:209], v[66:69]
	s_barrier
; #define PG8_STAGE(bufoff, gbase, voff) do { _Pragma("unroll") for (int _i = 0; _i < 2; ++_i) \
;         __builtin_amdgcn_global_load_lds((const unsigned*)((const char*)(gbase) + (voff)[_i]), (PG8_LAS unsigned*)(lds + (bufoff) + ldsw + _i * 8192), 16, 0, 0); } while (0)
; #define PG8_LDA(dst, b, h) do { _Pragma("unroll") for (int m = 0; m < 4; ++m) _Pragma("unroll") for (int k = 0; k < 2; ++k) dst[m][k] = *(const PG8_LAS bf16x8*)(lds + PG8_SA(b, h) + aoff + m * 2048 + k * 1024); } while (0)
; #define PG8_MMA(ai, bj, At, Bt) do { __builtin_amdgcn_s_setprio(1); _Pragma("unroll") for (int m = 0; m < 4; ++m) _Pragma("unroll") for (int n = 0; n < 2; ++n) _Pragma("unroll") for (int k = 0; k < 2; ++k) \
;         acc[ai][bj][m][n] = __builtin_amdgcn_mfma_f32_16x16x32_bf16(Bt[n][k], At[m][k], acc[ai][bj][m][n], 0, 0, 0); __builtin_amdgcn_s_setprio(0); } while (0)
; #define PG8_WAIT_V(n) asm volatile("s_waitcnt vmcnt(" #n ")" ::: "memory")
; #define PG8_WAIT_L(n) asm volatile("s_waitcnt lgkmcnt(" #n ")" ::: "memory")
; #define PG8_BAR __builtin_amdgcn_s_barrier()
; #define PG8_SCHED __builtin_amdgcn_sched_barrier(0)
; template <class Epi, class Sched, bool ALIGN_EPI = false, bool SP2 = false>
; __device__ __forceinline__ void gemm_phase(PG8_LAS unsigned char* lds, const Gemm g, const Sched& S, const Epi& E) {
;     ...
;         for (int t = 0; t < nt; t += 2) {
;             const bool last = (t == nt - 2);
;             const char* a1 = cA + (size_t)(t + 1) * kstep;
;             const char* a2 = last ? nA : cA + (size_t)(t + 2) * kstep; const char* b2 = last ? nB : cB + (size_t)(t + 2) * kstep;
;             const char* a3 = a2 + kstep; const char* b3 = b2 + kstep;
;     ...
;             PG8_LDA(At, 1, 1); PG8_STAGE(PG8_SB(1, 0), b3, voffB); PG8_STAGE(PG8_SB(1, 1), b3 + hstep, voffB); PG8_STAGE(PG8_SA(1, 0), a3, voffA);
;             PG8_WAIT_V(8); PG8_WAIT_L(0); PG8_BAR; PG8_MMA(1, 0, At, B0); PG8_MMA(1, 1, At, B1); PG8_BAR; PG8_SCHED;
	s_setprio 0
	s_add_i32 s40, s55, s4
	v_lshl_add_u64 v[140:141], v[140:141], 0, s[34:35]
	s_mov_b32 m0, s40
	ds_read_b128 v[178:181], v145 offset:49152
	ds_read_b128 v[182:185], v145 offset:50176
	ds_read_b128 v[186:189], v145 offset:51200
	ds_read_b128 v[190:193], v145 offset:52224
	ds_read_b128 v[194:197], v145 offset:53248
	ds_read_b128 v[198:201], v145 offset:54272
	ds_read_b128 v[202:205], v145 offset:55296
	ds_read_b128 v[206:209], v145 offset:56320
	global_load_lds_dwordx4 v[140:141], off
	s_add_i32 m0, s40, 0x2000
	s_add_u32 s10, s10, 0x80080
	v_lshl_add_u64 v[140:141], v[210:211], 0, s[34:35]
	s_addc_u32 s11, s11, 0
	s_add_i32 s40, s56, s4
	global_load_lds_dwordx4 v[140:141], off
	v_lshl_add_u64 v[140:141], s[10:11], 0, v[0:1]
	s_mov_b32 m0, s40
	s_nop 0
	global_load_lds_dwordx4 v[140:141], off
	v_lshl_add_u64 v[140:141], s[10:11], 0, v[134:135]
	s_add_i32 m0, s40, 0x2000
	s_nop 0
	global_load_lds_dwordx4 v[140:141], off
	v_lshl_add_u64 v[140:141], v[212:213], 0, s[34:35]
	s_mov_b32 m0, s43
	s_nop 0
	global_load_lds_dwordx4 v[140:141], off
	v_lshl_add_u64 v[140:141], v[214:215], 0, s[34:35]
	s_mov_b32 m0, s44
	s_nop 0
	global_load_lds_dwordx4 v[140:141], off
	s_waitcnt vmcnt(8)
	s_waitcnt lgkmcnt(0)
	s_setprio 1
	s_barrier
	v_mfma_f32_16x16x32_bf16 v[62:65], v[146:149], v[178:181], v[62:65]
	v_mfma_f32_16x16x32_bf16 v[58:61], v[154:157], v[178:181], v[58:61]
	v_mfma_f32_16x16x32_bf16 v[54:57], v[146:149], v[186:189], v[54:57]
	v_mfma_f32_16x16x32_bf16 v[46:49], v[154:157], v[186:189], v[46:49]
	v_mfma_f32_16x16x32_bf16 v[38:41], v[146:149], v[194:197], v[38:41]
	v_mfma_f32_16x16x32_bf16 v[30:33], v[154:157], v[194:197], v[30:33]
	v_mfma_f32_16x16x32_bf16 v[22:25], v[146:149], v[202:205], v[22:25]
	v_mfma_f32_16x16x32_bf16 v[14:17], v[154:157], v[202:205], v[14:17]
	v_mfma_f32_16x16x32_bf16 v[62:65], v[150:153], v[182:185], v[62:65]
	v_mfma_f32_16x16x32_bf16 v[58:61], v[158:161], v[182:185], v[58:61]
	v_mfma_f32_16x16x32_bf16 v[54:57], v[150:153], v[190:193], v[54:57]
	v_mfma_f32_16x16x32_bf16 v[46:49], v[158:161], v[190:193], v[46:49]
	v_mfma_f32_16x16x32_bf16 v[38:41], v[150:153], v[198:201], v[38:41]
	v_mfma_f32_16x16x32_bf16 v[30:33], v[158:161], v[198:201], v[30:33]
	v_mfma_f32_16x16x32_bf16 v[22:25], v[150:153], v[206:209], v[22:25]
	v_mfma_f32_16x16x32_bf16 v[14:17], v[158:161], v[206:209], v[14:17]
	s_setprio 0
	s_setprio 1
	v_mfma_f32_16x16x32_bf16 v[50:53], v[162:165], v[178:181], v[50:53]
	v_mfma_f32_16x16x32_bf16 v[42:45], v[170:173], v[178:181], v[42:45]
	v_mfma_f32_16x16x32_bf16 v[34:37], v[162:165], v[186:189], v[34:37]
	v_mfma_f32_16x16x32_bf16 v[26:29], v[170:173], v[186:189], v[26:29]
	v_mfma_f32_16x16x32_bf16 v[18:21], v[162:165], v[194:197], v[18:21]
	v_mfma_f32_16x16x32_bf16 v[10:13], v[170:173], v[194:197], v[10:13]
	v_mfma_f32_16x16x32_bf16 v[6:9], v[162:165], v[202:205], v[6:9]
	v_mfma_f32_16x16x32_bf16 v[2:5], v[170:173], v[202:205], v[2:5]
	v_mfma_f32_16x16x32_bf16 v[50:53], v[166:169], v[182:185], v[50:53]
	v_mfma_f32_16x16x32_bf16 v[42:45], v[174:177], v[182:185], v[42:45]
	v_mfma_f32_16x16x32_bf16 v[34:37], v[166:169], v[190:193], v[34:37]
	v_mfma_f32_16x16x32_bf16 v[26:29], v[174:177], v[190:193], v[26:29]
	v_mfma_f32_16x16x32_bf16 v[18:21], v[166:169], v[198:201], v[18:21]
	v_mfma_f32_16x16x32_bf16 v[10:13], v[174:177], v[198:201], v[10:13]
	v_mfma_f32_16x16x32_bf16 v[6:9], v[166:169], v[206:209], v[6:9]
	v_mfma_f32_16x16x32_bf16 v[2:5], v[174:177], v[206:209], v[2:5]
	s_barrier
	s_setprio 0
	s_add_i32 s54, s54, 2
	s_add_u32 s36, s36, 0x100
	s_addc_u32 s37, s37, 0
	s_add_u32 s52, s52, 0x100
	s_addc_u32 s53, s53, 0
	s_cmp_gt_u32 s54, 29
	s_cbranch_scc0 .LBB0_599
	s_and_b64 vcc, exec, s[12:13]
	s_cbranch_vccz .LBB0_602
	s_barrier
